# all K-loop s_setprio flips removed; one static s_setprio 1 for waves 0-3 during GEMM phases (reset at the grid barrier)
# speedup vs baseline: 1.0009x; 1.0009x over previous
; __global__ void __launch_bounds__(512, 2) mega_fwd(Args args) {
;     ...
;         const int wave = __builtin_amdgcn_readfirstlane(threadIdx.x >> 6);
;     ...
;                 const int l = r / 9, k = r - l * 9;
;                 const bf16_t* WL = Wb + (size_t)l * W_LAYER_ELEMS;
;                 if (k == 0 || k == 7) {
.Lwpf_skip:
	s_cmp_eq_u32 s1, 3
	s_cbranch_scc1 .Lsp_skip
	s_cmp_eq_u32 s1, 4
	s_cbranch_scc1 .Lsp_skip
	s_lshr_b32 s8, s24, 6
	s_cmp_ge_u32 s8, 4
	s_cbranch_scc1 .Lsp_skip
	s_setprio 1

; #define PG8_STAGE(bufoff, gbase, voff) do { _Pragma("unroll") for (int _i = 0; _i < 2; ++_i) \
;         __builtin_amdgcn_global_load_lds((const unsigned*)((const char*)(gbase) + (voff)[_i]), (LAS unsigned*)(lds + (bufoff) + ldsw + _i * 8192), 16, 0, 0); } while (0)
; #define PG8_LDA(dst, b, h) do { _Pragma("unroll") for (int m = 0; m < 4; ++m) _Pragma("unroll") for (int k = 0; k < 2; ++k) dst[m][k] = *(const LAS bf16x8*)(lds + PG8_SA(b, h) + aoff + m * 2048 + k * 1024); } while (0)
; #define PG8_LDB(dst, b, h) do { _Pragma("unroll") for (int n = 0; n < 2; ++n) _Pragma("unroll") for (int k = 0; k < 2; ++k) dst[n][k] = *(const LAS bf16x8*)(lds + PG8_SB(b, h) + boff + n * 2048 + k * 1024); } while (0)
; #define PG8_WAIT_V(n) asm volatile("s_waitcnt vmcnt(" #n ")" ::: "memory")
; #define PG8_WAIT_L(n) asm volatile("s_waitcnt lgkmcnt(" #n ")" ::: "memory")
; #define PG8_BAR __builtin_amdgcn_s_barrier()
; #define PG8_SCHED __builtin_amdgcn_sched_barrier(0)
; template <class Epi>
; __device__ __forceinline__ void gemm_phase(LAS unsigned char* lds, const Gemm g, const Order& S, const Epi& E) {
;     ...
;             const bool last = (t == nt - 2);
;             const char* a1 = cA + (size_t)(t + 1) * kstep;
;             const char* a2 = last ? nA : cA + (size_t)(t + 2) * kstep; const char* b2 = last ? nB : cB + (size_t)(t + 2) * kstep;
;             const char* a3 = a2 + kstep; const char* b3 = b2 + kstep;
;             PG8_LDB(B0, 0, 0); PG8_LDB(B1, 0, 1); PG8_SCHED; PG8_LDA(At, 0, 0); PG8_STAGE(PG8_SA(1, 1), a1 + hstepA, voffA);
;             PG8_WAIT_V(8); PG8_WAIT_L(0); PG8_BAR; PG8_MMA(0, 0, At, B0); PG8_MMA(0, 1, At, B1); PG8_BAR; PG8_SCHED;
;             PG8_LDA(At, 0, 1); PG8_STAGE(PG8_SB(0, 0), b2, voffB); PG8_STAGE(PG8_SB(0, 1), b2 + hstepB, voffB); PG8_STAGE(PG8_SA(0, 0), a2, voffA);
;             PG8_WAIT_V(8); PG8_WAIT_L(0); PG8_BAR; PG8_MMA(1, 0, At, B0); PG8_MMA(1, 1, At, B1); PG8_BAR; PG8_SCHED;
.LBB0_81:
	s_add_u32 s4, s40, 0xfffc0080
	s_addc_u32 s5, s41, -1
	s_add_i32 s6, 0, 0x10000
	s_cmp_eq_u32 vcc_lo, 12
	s_cselect_b32 s71, s34, s5
	s_cselect_b32 s70, s35, s4
	v_add_u32_e32 v142, s6, v145
	s_cselect_b32 s69, s45, s89
	s_cselect_b32 s68, s47, s88
	s_add_i32 s7, 0, 0x14000
	ds_read_b128 v[138:141], v142
	ds_read_b128 v[148:151], v142 offset:1024
	ds_read_b128 v[152:155], v142 offset:2048
	ds_read_b128 v[156:159], v142 offset:3072
	v_add_u32_e32 v142, s7, v145
	ds_read_b128 v[172:175], v142
	ds_read_b128 v[176:179], v142 offset:1024
	ds_read_b128 v[180:183], v142 offset:2048
	ds_read_b128 v[184:187], v142 offset:3072
	v_lshl_add_u64 v[142:143], s[40:41], 0, v[134:135]
	s_add_i32 m0, s24, 0xc000
	ds_read_b128 v[188:191], v147
	ds_read_b128 v[192:195], v147 offset:1024
	ds_read_b128 v[214:217], v147 offset:2048
	ds_read_b128 v[218:221], v147 offset:3072
	ds_read_b128 v[222:225], v147 offset:4096
	ds_read_b128 v[226:229], v147 offset:5120
	ds_read_b128 v[230:233], v147 offset:6144
	ds_read_b128 v[234:237], v147 offset:7168
	global_load_lds_dwordx4 v[142:143], off
	v_lshl_add_u64 v[142:143], s[40:41], 0, v[136:137]
	s_add_i32 m0, s24, 0xe000
	s_nop 0
	global_load_lds_dwordx4 v[142:143], off
	s_waitcnt vmcnt(8)
	s_waitcnt lgkmcnt(0)
	s_barrier
	v_mfma_f32_16x16x32_f16 v[124:127], v[138:141], v[188:191], v[124:127]
	v_mfma_f32_16x16x32_f16 v[120:123], v[152:155], v[188:191], v[120:123]
	v_mfma_f32_16x16x32_f16 v[108:111], v[138:141], v[214:217], v[108:111]
	v_mfma_f32_16x16x32_f16 v[104:107], v[152:155], v[214:217], v[104:107]
	v_mfma_f32_16x16x32_f16 v[92:95], v[138:141], v[222:225], v[92:95]
	v_mfma_f32_16x16x32_f16 v[88:91], v[152:155], v[222:225], v[88:91]
	v_mfma_f32_16x16x32_f16 v[76:79], v[138:141], v[230:233], v[76:79]
	v_mfma_f32_16x16x32_f16 v[72:75], v[152:155], v[230:233], v[72:75]
	v_mfma_f32_16x16x32_f16 v[124:127], v[148:151], v[192:195], v[124:127]
	v_mfma_f32_16x16x32_f16 v[120:123], v[156:159], v[192:195], v[120:123]
	v_mfma_f32_16x16x32_f16 v[108:111], v[148:151], v[218:221], v[108:111]
	v_mfma_f32_16x16x32_f16 v[104:107], v[156:159], v[218:221], v[104:107]
	v_mfma_f32_16x16x32_f16 v[92:95], v[148:151], v[226:229], v[92:95]
	v_mfma_f32_16x16x32_f16 v[88:91], v[156:159], v[226:229], v[88:91]
	v_mfma_f32_16x16x32_f16 v[76:79], v[148:151], v[234:237], v[76:79]
	v_mfma_f32_16x16x32_f16 v[72:75], v[156:159], v[234:237], v[72:75]
	v_mfma_f32_16x16x32_f16 v[116:119], v[172:175], v[188:191], v[116:119]
	v_mfma_f32_16x16x32_f16 v[112:115], v[180:183], v[188:191], v[112:115]
	v_mfma_f32_16x16x32_f16 v[100:103], v[172:175], v[214:217], v[100:103]
	v_mfma_f32_16x16x32_f16 v[96:99], v[180:183], v[214:217], v[96:99]
	v_mfma_f32_16x16x32_f16 v[84:87], v[172:175], v[222:225], v[84:87]
	v_mfma_f32_16x16x32_f16 v[80:83], v[180:183], v[222:225], v[80:83]
	v_mfma_f32_16x16x32_f16 v[68:71], v[172:175], v[230:233], v[68:71]
	v_mfma_f32_16x16x32_f16 v[64:67], v[180:183], v[230:233], v[64:67]
	v_mfma_f32_16x16x32_f16 v[116:119], v[176:179], v[192:195], v[116:119]
	v_mfma_f32_16x16x32_f16 v[112:115], v[184:187], v[192:195], v[112:115]
	v_mfma_f32_16x16x32_f16 v[100:103], v[176:179], v[218:221], v[100:103]
	v_mfma_f32_16x16x32_f16 v[96:99], v[184:187], v[218:221], v[96:99]
	v_mfma_f32_16x16x32_f16 v[84:87], v[176:179], v[226:229], v[84:87]
	v_mfma_f32_16x16x32_f16 v[80:83], v[184:187], v[226:229], v[80:83]
	v_mfma_f32_16x16x32_f16 v[68:71], v[176:179], v[234:237], v[68:71]
	v_mfma_f32_16x16x32_f16 v[64:67], v[184:187], v[234:237], v[64:67]
	s_barrier
	s_add_i32 s4, s6, s23
	v_lshl_add_u64 v[142:143], s[68:69], 0, v[160:161]
	s_mov_b32 m0, s4
	ds_read_b128 v[188:191], v147 offset:16384
	ds_read_b128 v[192:195], v147 offset:17408
	ds_read_b128 v[214:217], v147 offset:18432
	ds_read_b128 v[218:221], v147 offset:19456
	ds_read_b128 v[222:225], v147 offset:20480
	ds_read_b128 v[226:229], v147 offset:21504
	ds_read_b128 v[230:233], v147 offset:22528
	ds_read_b128 v[234:237], v147 offset:23552
	global_load_lds_dwordx4 v[142:143], off
	s_add_i32 m0, s4, 0x2000
	s_add_u32 s4, s68, 0x40000
	v_lshl_add_u64 v[200:201], s[68:69], 0, v[128:129]
	s_addc_u32 s5, s69, 0
	s_add_i32 s6, s7, s23
	global_load_lds_dwordx4 v[200:201], off
	v_lshl_add_u64 v[238:239], s[4:5], 0, v[160:161]
	s_mov_b32 m0, s6
	v_lshl_add_u64 v[240:241], s[70:71], 0, v[130:131]
	global_load_lds_dwordx4 v[238:239], off
	v_lshl_add_u64 v[238:239], s[4:5], 0, v[128:129]
	s_add_i32 m0, s6, 0x2000
	s_nop 0
	global_load_lds_dwordx4 v[238:239], off
	v_lshl_add_u64 v[238:239], s[70:71], 0, v[132:133]
	s_mov_b32 m0, s24
	s_nop 0
	global_load_lds_dwordx4 v[238:239], off
	s_mov_b32 m0, s25
	s_nop 0
	global_load_lds_dwordx4 v[240:241], off
	s_waitcnt vmcnt(8)
	s_waitcnt lgkmcnt(0)
	s_barrier
; #define PG8_STAGE(bufoff, gbase, voff) do { _Pragma("unroll") for (int _i = 0; _i < 2; ++_i) \
;         __builtin_amdgcn_global_load_lds((const unsigned*)((const char*)(gbase) + (voff)[_i]), (LAS unsigned*)(lds + (bufoff) + ldsw + _i * 8192), 16, 0, 0); } while (0)
; #define PG8_LDA(dst, b, h) do { _Pragma("unroll") for (int m = 0; m < 4; ++m) _Pragma("unroll") for (int k = 0; k < 2; ++k) dst[m][k] = *(const LAS bf16x8*)(lds + PG8_SA(b, h) + aoff + m * 2048 + k * 1024); } while (0)
; #define PG8_LDB(dst, b, h) do { _Pragma("unroll") for (int n = 0; n < 2; ++n) _Pragma("unroll") for (int k = 0; k < 2; ++k) dst[n][k] = *(const LAS bf16x8*)(lds + PG8_SB(b, h) + boff + n * 2048 + k * 1024); } while (0)
; #define PG8_WAIT_V(n) asm volatile("s_waitcnt vmcnt(" #n ")" ::: "memory")
; #define PG8_WAIT_L(n) asm volatile("s_waitcnt lgkmcnt(" #n ")" ::: "memory")
; #define PG8_BAR __builtin_amdgcn_s_barrier()
; #define PG8_SCHED __builtin_amdgcn_sched_barrier(0)
; template <class Epi>
; __device__ __forceinline__ void gemm_phase(LAS unsigned char* lds, const Gemm g, const Order& S, const Epi& E) {
;     ...
;             PG8_WAIT_V(8); PG8_WAIT_L(0); PG8_BAR; PG8_MMA(1, 0, At, B0); PG8_MMA(1, 1, At, B1); PG8_BAR; PG8_SCHED;
;             PG8_LDB(B0, 1, 0); PG8_LDB(B1, 1, 1); PG8_SCHED; PG8_LDA(At, 1, 0); PG8_STAGE(PG8_SA(0, 1), a2 + hstepA, voffA);
;             PG8_WAIT_V(8); PG8_WAIT_L(0); PG8_BAR; PG8_MMA(0, 0, At, B0); PG8_MMA(0, 1, At, B1); PG8_BAR; PG8_SCHED;
	v_mfma_f32_16x16x32_f16 v[60:63], v[138:141], v[188:191], v[60:63]
	v_mfma_f32_16x16x32_f16 v[56:59], v[152:155], v[188:191], v[56:59]
	v_mfma_f32_16x16x32_f16 v[44:47], v[138:141], v[214:217], v[44:47]
	v_mfma_f32_16x16x32_f16 v[40:43], v[152:155], v[214:217], v[40:43]
	v_mfma_f32_16x16x32_f16 v[28:31], v[138:141], v[222:225], v[28:31]
	v_mfma_f32_16x16x32_f16 v[24:27], v[152:155], v[222:225], v[24:27]
	v_mfma_f32_16x16x32_f16 v[12:15], v[138:141], v[230:233], v[12:15]
	v_mfma_f32_16x16x32_f16 v[8:11], v[152:155], v[230:233], v[8:11]
	v_mfma_f32_16x16x32_f16 v[60:63], v[148:151], v[192:195], v[60:63]
	v_mfma_f32_16x16x32_f16 v[56:59], v[156:159], v[192:195], v[56:59]
	v_mfma_f32_16x16x32_f16 v[44:47], v[148:151], v[218:221], v[44:47]
	v_mfma_f32_16x16x32_f16 v[40:43], v[156:159], v[218:221], v[40:43]
	v_mfma_f32_16x16x32_f16 v[28:31], v[148:151], v[226:229], v[28:31]
	v_mfma_f32_16x16x32_f16 v[24:27], v[156:159], v[226:229], v[24:27]
	v_mfma_f32_16x16x32_f16 v[12:15], v[148:151], v[234:237], v[12:15]
	v_mfma_f32_16x16x32_f16 v[8:11], v[156:159], v[234:237], v[8:11]
	v_mfma_f32_16x16x32_f16 v[52:55], v[172:175], v[188:191], v[52:55]
	v_mfma_f32_16x16x32_f16 v[48:51], v[180:183], v[188:191], v[48:51]
	v_mfma_f32_16x16x32_f16 v[36:39], v[172:175], v[214:217], v[36:39]
	v_mfma_f32_16x16x32_f16 v[32:35], v[180:183], v[214:217], v[32:35]
	v_mfma_f32_16x16x32_f16 v[20:23], v[172:175], v[222:225], v[20:23]
	v_mfma_f32_16x16x32_f16 v[16:19], v[180:183], v[222:225], v[16:19]
	v_mfma_f32_16x16x32_f16 v[4:7], v[172:175], v[230:233], v[4:7]
	v_mfma_f32_16x16x32_f16 v[0:3], v[180:183], v[230:233], v[0:3]
	v_mfma_f32_16x16x32_f16 v[52:55], v[176:179], v[192:195], v[52:55]
	v_mfma_f32_16x16x32_f16 v[48:51], v[184:187], v[192:195], v[48:51]
	v_mfma_f32_16x16x32_f16 v[36:39], v[176:179], v[218:221], v[36:39]
	v_mfma_f32_16x16x32_f16 v[32:35], v[184:187], v[218:221], v[32:35]
	v_mfma_f32_16x16x32_f16 v[20:23], v[176:179], v[226:229], v[20:23]
	v_mfma_f32_16x16x32_f16 v[16:19], v[184:187], v[226:229], v[16:19]
	v_mfma_f32_16x16x32_f16 v[4:7], v[176:179], v[234:237], v[4:7]
	v_mfma_f32_16x16x32_f16 v[0:3], v[184:187], v[234:237], v[0:3]
	s_barrier
	s_add_i32 s6, 0, 0x18000
	s_add_i32 s7, 0, 0x1c000
	v_add_u32_e32 v156, s6, v145
	v_add_u32_e32 v171, s7, v145
	ds_read_b128 v[138:141], v156
	ds_read_b128 v[148:151], v156 offset:1024
	ds_read_b128 v[152:155], v156 offset:2048
	ds_read_b128 v[156:159], v156 offset:3072
	ds_read_b128 v[172:175], v171
	ds_read_b128 v[176:179], v171 offset:1024
	ds_read_b128 v[180:183], v171 offset:2048
	ds_read_b128 v[184:187], v171 offset:3072
	s_add_u32 s4, s70, 0x40000
	s_addc_u32 s5, s71, 0
	s_mov_b32 m0, s26
	v_lshl_add_u64 v[242:243], s[4:5], 0, v[132:133]
	ds_read_b128 v[188:191], v147 offset:32768
	ds_read_b128 v[192:195], v147 offset:33792
	ds_read_b128 v[214:217], v147 offset:34816
	ds_read_b128 v[218:221], v147 offset:35840
	ds_read_b128 v[222:225], v147 offset:36864
	ds_read_b128 v[226:229], v147 offset:37888
	ds_read_b128 v[230:233], v147 offset:38912
	ds_read_b128 v[234:237], v147 offset:39936
	global_load_lds_dwordx4 v[242:243], off
	v_lshl_add_u64 v[242:243], s[4:5], 0, v[130:131]
	s_mov_b32 m0, s27
	s_nop 0
	global_load_lds_dwordx4 v[242:243], off
	s_waitcnt vmcnt(8)
	s_waitcnt lgkmcnt(0)
	s_barrier
	v_mfma_f32_16x16x32_f16 v[124:127], v[138:141], v[188:191], v[124:127]
	v_mfma_f32_16x16x32_f16 v[120:123], v[152:155], v[188:191], v[120:123]
	v_mfma_f32_16x16x32_f16 v[108:111], v[138:141], v[214:217], v[108:111]
	v_mfma_f32_16x16x32_f16 v[104:107], v[152:155], v[214:217], v[104:107]
	v_mfma_f32_16x16x32_f16 v[92:95], v[138:141], v[222:225], v[92:95]
	v_mfma_f32_16x16x32_f16 v[88:91], v[152:155], v[222:225], v[88:91]
	v_mfma_f32_16x16x32_f16 v[76:79], v[138:141], v[230:233], v[76:79]
	v_mfma_f32_16x16x32_f16 v[72:75], v[152:155], v[230:233], v[72:75]
	v_mfma_f32_16x16x32_f16 v[124:127], v[148:151], v[192:195], v[124:127]
	v_mfma_f32_16x16x32_f16 v[120:123], v[156:159], v[192:195], v[120:123]
	v_mfma_f32_16x16x32_f16 v[108:111], v[148:151], v[218:221], v[108:111]
	v_mfma_f32_16x16x32_f16 v[104:107], v[156:159], v[218:221], v[104:107]
	v_mfma_f32_16x16x32_f16 v[92:95], v[148:151], v[226:229], v[92:95]
	v_mfma_f32_16x16x32_f16 v[88:91], v[156:159], v[226:229], v[88:91]
	v_mfma_f32_16x16x32_f16 v[76:79], v[148:151], v[234:237], v[76:79]
	v_mfma_f32_16x16x32_f16 v[72:75], v[156:159], v[234:237], v[72:75]
	v_mfma_f32_16x16x32_f16 v[116:119], v[172:175], v[188:191], v[116:119]
	v_mfma_f32_16x16x32_f16 v[112:115], v[180:183], v[188:191], v[112:115]
	v_mfma_f32_16x16x32_f16 v[100:103], v[172:175], v[214:217], v[100:103]
	v_mfma_f32_16x16x32_f16 v[96:99], v[180:183], v[214:217], v[96:99]
	v_mfma_f32_16x16x32_f16 v[84:87], v[172:175], v[222:225], v[84:87]
	v_mfma_f32_16x16x32_f16 v[80:83], v[180:183], v[222:225], v[80:83]
	v_mfma_f32_16x16x32_f16 v[68:71], v[172:175], v[230:233], v[68:71]
	v_mfma_f32_16x16x32_f16 v[64:67], v[180:183], v[230:233], v[64:67]
	v_mfma_f32_16x16x32_f16 v[116:119], v[176:179], v[192:195], v[116:119]
	v_mfma_f32_16x16x32_f16 v[112:115], v[184:187], v[192:195], v[112:115]
	v_mfma_f32_16x16x32_f16 v[100:103], v[176:179], v[218:221], v[100:103]
	v_mfma_f32_16x16x32_f16 v[96:99], v[184:187], v[218:221], v[96:99]
	v_mfma_f32_16x16x32_f16 v[84:87], v[176:179], v[226:229], v[84:87]
	v_mfma_f32_16x16x32_f16 v[80:83], v[184:187], v[226:229], v[80:83]
	v_mfma_f32_16x16x32_f16 v[68:71], v[176:179], v[234:237], v[68:71]
	v_mfma_f32_16x16x32_f16 v[64:67], v[184:187], v[234:237], v[64:67]
	s_barrier
; #define PG8_STAGE(bufoff, gbase, voff) do { _Pragma("unroll") for (int _i = 0; _i < 2; ++_i) \
;         __builtin_amdgcn_global_load_lds((const unsigned*)((const char*)(gbase) + (voff)[_i]), (LAS unsigned*)(lds + (bufoff) + ldsw + _i * 8192), 16, 0, 0); } while (0)
; #define PG8_LDA(dst, b, h) do { _Pragma("unroll") for (int m = 0; m < 4; ++m) _Pragma("unroll") for (int k = 0; k < 2; ++k) dst[m][k] = *(const LAS bf16x8*)(lds + PG8_SA(b, h) + aoff + m * 2048 + k * 1024); } while (0)
; #define PG8_WAIT_V(n) asm volatile("s_waitcnt vmcnt(" #n ")" ::: "memory")
; #define PG8_WAIT_L(n) asm volatile("s_waitcnt lgkmcnt(" #n ")" ::: "memory")
; #define PG8_BAR __builtin_amdgcn_s_barrier()
; #define PG8_SCHED __builtin_amdgcn_sched_barrier(0)
; template <class Epi>
; __device__ __forceinline__ void gemm_phase(LAS unsigned char* lds, const Gemm g, const Order& S, const Epi& E) {
;     ...
;             PG8_LDA(At, 1, 1); PG8_STAGE(PG8_SB(1, 0), b3, voffB); PG8_STAGE(PG8_SB(1, 1), b3 + hstepB, voffB); PG8_STAGE(PG8_SA(1, 0), a3, voffA);
;             PG8_WAIT_V(8); PG8_WAIT_L(0); PG8_BAR; PG8_MMA(1, 0, At, B0); PG8_MMA(1, 1, At, B1); PG8_BAR; PG8_SCHED;
;         }
;         if constexpr (ALIGN_EPI) { if (wr == 0) PG8_BAR; }
;         if constexpr (!Epi::AFTER_DRAIN) E(acc, cur, wr, wc, fr, fq);
;         if (!has_next) break;
	s_add_i32 s4, s6, s23
	v_lshl_add_u64 v[142:143], v[142:143], 0, s[62:63]
	s_mov_b32 m0, s4
	ds_read_b128 v[188:191], v147 offset:49152
	ds_read_b128 v[192:195], v147 offset:50176
	ds_read_b128 v[214:217], v147 offset:51200
	ds_read_b128 v[218:221], v147 offset:52224
	ds_read_b128 v[222:225], v147 offset:53248
	ds_read_b128 v[226:229], v147 offset:54272
	ds_read_b128 v[230:233], v147 offset:55296
	ds_read_b128 v[234:237], v147 offset:56320
	global_load_lds_dwordx4 v[142:143], off
	s_add_i32 m0, s4, 0x2000
	s_add_u32 s4, s68, 0x40080
	v_lshl_add_u64 v[142:143], v[200:201], 0, s[62:63]
	s_addc_u32 s5, s69, 0
	s_add_i32 s6, s7, s23
	global_load_lds_dwordx4 v[142:143], off
	v_lshl_add_u64 v[142:143], s[4:5], 0, v[160:161]
	s_mov_b32 m0, s6
	s_nop 0
	global_load_lds_dwordx4 v[142:143], off
	v_lshl_add_u64 v[142:143], s[4:5], 0, v[128:129]
	s_add_i32 m0, s6, 0x2000
	s_nop 0
	global_load_lds_dwordx4 v[142:143], off
	v_lshl_add_u64 v[142:143], v[238:239], 0, s[62:63]
	s_mov_b32 m0, s28
	s_nop 0
	global_load_lds_dwordx4 v[142:143], off
	v_lshl_add_u64 v[142:143], v[240:241], 0, s[62:63]
	s_mov_b32 m0, s29
	s_nop 0
	global_load_lds_dwordx4 v[142:143], off
	s_waitcnt vmcnt(8)
	s_waitcnt lgkmcnt(0)
	s_barrier
	v_mfma_f32_16x16x32_f16 v[60:63], v[138:141], v[188:191], v[60:63]
	v_mfma_f32_16x16x32_f16 v[56:59], v[152:155], v[188:191], v[56:59]
	v_mfma_f32_16x16x32_f16 v[44:47], v[138:141], v[214:217], v[44:47]
	v_mfma_f32_16x16x32_f16 v[40:43], v[152:155], v[214:217], v[40:43]
	v_mfma_f32_16x16x32_f16 v[28:31], v[138:141], v[222:225], v[28:31]
	v_mfma_f32_16x16x32_f16 v[24:27], v[152:155], v[222:225], v[24:27]
	v_mfma_f32_16x16x32_f16 v[12:15], v[138:141], v[230:233], v[12:15]
	v_mfma_f32_16x16x32_f16 v[8:11], v[152:155], v[230:233], v[8:11]
	v_mfma_f32_16x16x32_f16 v[60:63], v[148:151], v[192:195], v[60:63]
	v_mfma_f32_16x16x32_f16 v[56:59], v[156:159], v[192:195], v[56:59]
	v_mfma_f32_16x16x32_f16 v[44:47], v[148:151], v[218:221], v[44:47]
	v_mfma_f32_16x16x32_f16 v[40:43], v[156:159], v[218:221], v[40:43]
	v_mfma_f32_16x16x32_f16 v[28:31], v[148:151], v[226:229], v[28:31]
	v_mfma_f32_16x16x32_f16 v[24:27], v[156:159], v[226:229], v[24:27]
	v_mfma_f32_16x16x32_f16 v[12:15], v[148:151], v[234:237], v[12:15]
	v_mfma_f32_16x16x32_f16 v[8:11], v[156:159], v[234:237], v[8:11]
	v_mfma_f32_16x16x32_f16 v[52:55], v[172:175], v[188:191], v[52:55]
	v_mfma_f32_16x16x32_f16 v[48:51], v[180:183], v[188:191], v[48:51]
	v_mfma_f32_16x16x32_f16 v[36:39], v[172:175], v[214:217], v[36:39]
	v_mfma_f32_16x16x32_f16 v[32:35], v[180:183], v[214:217], v[32:35]
	v_mfma_f32_16x16x32_f16 v[20:23], v[172:175], v[222:225], v[20:23]
	v_mfma_f32_16x16x32_f16 v[16:19], v[180:183], v[222:225], v[16:19]
	v_mfma_f32_16x16x32_f16 v[4:7], v[172:175], v[230:233], v[4:7]
	v_mfma_f32_16x16x32_f16 v[0:3], v[180:183], v[230:233], v[0:3]
	v_mfma_f32_16x16x32_f16 v[52:55], v[176:179], v[192:195], v[52:55]
	v_mfma_f32_16x16x32_f16 v[48:51], v[184:187], v[192:195], v[48:51]
	v_mfma_f32_16x16x32_f16 v[36:39], v[176:179], v[218:221], v[36:39]
	v_mfma_f32_16x16x32_f16 v[32:35], v[184:187], v[218:221], v[32:35]
	v_mfma_f32_16x16x32_f16 v[20:23], v[176:179], v[226:229], v[20:23]
	v_mfma_f32_16x16x32_f16 v[16:19], v[184:187], v[226:229], v[16:19]
	v_mfma_f32_16x16x32_f16 v[4:7], v[176:179], v[234:237], v[4:7]
	v_mfma_f32_16x16x32_f16 v[0:3], v[184:187], v[234:237], v[0:3]
	s_barrier
	s_add_i32 vcc_lo, vcc_lo, 2
	s_add_u32 s40, s40, 0x100
	s_addc_u32 s41, s41, 0
	s_add_u32 s88, s88, 0x100
	s_addc_u32 s89, s89, 0
	s_cmp_gt_u32 vcc_lo, 13
	s_cbranch_scc0 .LBB0_81
	s_and_b64 vcc, exec, s[42:43]
	s_cbranch_vccz .LBB0_84
	s_barrier

; #define PG8_STAGE(bufoff, gbase, voff) do { _Pragma("unroll") for (int _i = 0; _i < 2; ++_i) \
;         __builtin_amdgcn_global_load_lds((const unsigned*)((const char*)(gbase) + (voff)[_i]), (LAS unsigned*)(lds + (bufoff) + ldsw + _i * 8192), 16, 0, 0); } while (0)
; #define PG8_LDA(dst, b, h) do { _Pragma("unroll") for (int m = 0; m < 4; ++m) _Pragma("unroll") for (int k = 0; k < 2; ++k) dst[m][k] = *(const LAS bf16x8*)(lds + PG8_SA(b, h) + aoff + m * 2048 + k * 1024); } while (0)
; #define PG8_LDB(dst, b, h) do { _Pragma("unroll") for (int n = 0; n < 2; ++n) _Pragma("unroll") for (int k = 0; k < 2; ++k) dst[n][k] = *(const LAS bf16x8*)(lds + PG8_SB(b, h) + boff + n * 2048 + k * 1024); } while (0)
; #define PG8_WAIT_V(n) asm volatile("s_waitcnt vmcnt(" #n ")" ::: "memory")
; #define PG8_WAIT_L(n) asm volatile("s_waitcnt lgkmcnt(" #n ")" ::: "memory")
; #define PG8_BAR __builtin_amdgcn_s_barrier()
; #define PG8_SCHED __builtin_amdgcn_sched_barrier(0)
; template <class Epi>
; __device__ __forceinline__ void gemm_phase(LAS unsigned char* lds, const Gemm g, const Order& S, const Epi& E) {
;     ...
;             const bool last = (t == nt - 2);
;             const char* a1 = cA + (size_t)(t + 1) * kstep;
;             const char* a2 = last ? nA : cA + (size_t)(t + 2) * kstep; const char* b2 = last ? nB : cB + (size_t)(t + 2) * kstep;
;             const char* a3 = a2 + kstep; const char* b3 = b2 + kstep;
;             PG8_LDB(B0, 0, 0); PG8_LDB(B1, 0, 1); PG8_SCHED; PG8_LDA(At, 0, 0); PG8_STAGE(PG8_SA(1, 1), a1 + hstepA, voffA);
;             PG8_WAIT_V(8); PG8_WAIT_L(0); PG8_BAR; PG8_MMA(0, 0, At, B0); PG8_MMA(0, 1, At, B1); PG8_BAR; PG8_SCHED;
;             PG8_LDA(At, 0, 1); PG8_STAGE(PG8_SB(0, 0), b2, voffB); PG8_STAGE(PG8_SB(0, 1), b2 + hstepB, voffB); PG8_STAGE(PG8_SA(0, 0), a2, voffA);
;             PG8_WAIT_V(8); PG8_WAIT_L(0); PG8_BAR; PG8_MMA(1, 0, At, B0); PG8_MMA(1, 1, At, B1); PG8_BAR; PG8_SCHED;
.LBB0_172:
	s_add_i32 s36, s35, 2
	s_add_u32 s4, s70, vcc_lo
	s_addc_u32 s5, s71, vcc_hi
	s_add_u32 s37, s68, vcc_lo
	s_addc_u32 s6, s69, vcc_hi
	s_add_i32 s7, 0, 0x10000
	s_cmp_eq_u32 s49, s35
	s_cselect_b32 s65, s45, s5
	s_cselect_b32 s64, s44, s4
	v_add_u32_e32 v158, s7, v143
	s_cselect_b32 s5, s89, s6
	s_cselect_b32 s4, s88, s37
	s_add_i32 s6, 0, 0x14000
	ds_read_b128 v[146:149], v158
	ds_read_b128 v[150:153], v158 offset:1024
	ds_read_b128 v[154:157], v158 offset:2048
	ds_read_b128 v[172:175], v158 offset:3072
	v_add_u32_e32 v158, s6, v143
	ds_read_b128 v[176:179], v158
	ds_read_b128 v[180:183], v158 offset:1024
	ds_read_b128 v[184:187], v158 offset:2048
	ds_read_b128 v[188:191], v158 offset:3072
	v_lshl_add_u64 v[158:159], s[70:71], 0, v[140:141]
	s_add_i32 m0, s67, 0xc000
	ds_read_b128 v[192:195], v144
	ds_read_b128 v[214:217], v144 offset:1024
	ds_read_b128 v[218:221], v144 offset:2048
	ds_read_b128 v[222:225], v144 offset:3072
	ds_read_b128 v[226:229], v144 offset:4096
	ds_read_b128 v[230:233], v144 offset:5120
	ds_read_b128 v[234:237], v144 offset:6144
	ds_read_b128 v[238:241], v144 offset:7168
	global_load_lds_dwordx4 v[158:159], off
	v_lshl_add_u64 v[158:159], s[70:71], 0, v[138:139]
	s_add_i32 m0, s67, 0xe000
	s_nop 0
	global_load_lds_dwordx4 v[158:159], off
	s_waitcnt vmcnt(8)
	s_waitcnt lgkmcnt(0)
	s_barrier
	v_mfma_f32_16x16x32_bf16 v[28:31], v[146:149], v[192:195], v[28:31]
	v_mfma_f32_16x16x32_bf16 v[24:27], v[154:157], v[192:195], v[24:27]
	v_mfma_f32_16x16x32_bf16 v[20:23], v[146:149], v[218:221], v[20:23]
	v_mfma_f32_16x16x32_bf16 v[16:19], v[154:157], v[218:221], v[16:19]
	v_mfma_f32_16x16x32_bf16 v[76:79], v[146:149], v[226:229], v[76:79]
	v_mfma_f32_16x16x32_bf16 v[72:75], v[154:157], v[226:229], v[72:75]
	v_mfma_f32_16x16x32_bf16 v[92:95], v[146:149], v[234:237], v[92:95]
	v_mfma_f32_16x16x32_bf16 v[88:91], v[154:157], v[234:237], v[88:91]
	v_mfma_f32_16x16x32_bf16 v[28:31], v[150:153], v[214:217], v[28:31]
	v_mfma_f32_16x16x32_bf16 v[24:27], v[172:175], v[214:217], v[24:27]
	v_mfma_f32_16x16x32_bf16 v[20:23], v[150:153], v[222:225], v[20:23]
	v_mfma_f32_16x16x32_bf16 v[16:19], v[172:175], v[222:225], v[16:19]
	v_mfma_f32_16x16x32_bf16 v[76:79], v[150:153], v[230:233], v[76:79]
	v_mfma_f32_16x16x32_bf16 v[72:75], v[172:175], v[230:233], v[72:75]
	v_mfma_f32_16x16x32_bf16 v[92:95], v[150:153], v[238:241], v[92:95]
	v_mfma_f32_16x16x32_bf16 v[88:91], v[172:175], v[238:241], v[88:91]
	v_mfma_f32_16x16x32_bf16 v[12:15], v[176:179], v[192:195], v[12:15]
	v_mfma_f32_16x16x32_bf16 v[8:11], v[184:187], v[192:195], v[8:11]
	v_mfma_f32_16x16x32_bf16 v[4:7], v[176:179], v[218:221], v[4:7]
	v_mfma_f32_16x16x32_bf16 v[0:3], v[184:187], v[218:221], v[0:3]
	v_mfma_f32_16x16x32_bf16 v[68:71], v[176:179], v[226:229], v[68:71]
	v_mfma_f32_16x16x32_bf16 v[64:67], v[184:187], v[226:229], v[64:67]
	v_mfma_f32_16x16x32_bf16 v[84:87], v[176:179], v[234:237], v[84:87]
	v_mfma_f32_16x16x32_bf16 v[80:83], v[184:187], v[234:237], v[80:83]
	v_mfma_f32_16x16x32_bf16 v[12:15], v[180:183], v[214:217], v[12:15]
	v_mfma_f32_16x16x32_bf16 v[8:11], v[188:191], v[214:217], v[8:11]
	v_mfma_f32_16x16x32_bf16 v[4:7], v[180:183], v[222:225], v[4:7]
	v_mfma_f32_16x16x32_bf16 v[0:3], v[188:191], v[222:225], v[0:3]
	v_mfma_f32_16x16x32_bf16 v[68:71], v[180:183], v[230:233], v[68:71]
	v_mfma_f32_16x16x32_bf16 v[64:67], v[188:191], v[230:233], v[64:67]
	v_mfma_f32_16x16x32_bf16 v[84:87], v[180:183], v[238:241], v[84:87]
	v_mfma_f32_16x16x32_bf16 v[80:83], v[188:191], v[238:241], v[80:83]
	s_barrier
	s_add_i32 s7, s7, s29
	v_lshl_add_u64 v[158:159], s[4:5], 0, v[160:161]
	s_mov_b32 m0, s7
	ds_read_b128 v[192:195], v144 offset:16384
	ds_read_b128 v[214:217], v144 offset:17408
	ds_read_b128 v[218:221], v144 offset:18432
	ds_read_b128 v[222:225], v144 offset:19456
	ds_read_b128 v[226:229], v144 offset:20480
	ds_read_b128 v[230:233], v144 offset:21504
	ds_read_b128 v[234:237], v144 offset:22528
	ds_read_b128 v[238:241], v144 offset:23552
	global_load_lds_dwordx4 v[158:159], off
	s_add_i32 m0, s7, 0x2000
	v_lshl_add_u64 v[242:243], s[4:5], 0, v[128:129]
	s_add_u32 s4, s4, s28
	s_addc_u32 s5, s5, 0
	s_add_i32 s6, s6, s29
	global_load_lds_dwordx4 v[242:243], off
	v_lshl_add_u64 v[244:245], s[4:5], 0, v[160:161]
	s_mov_b32 m0, s6
	v_lshl_add_u64 v[246:247], s[4:5], 0, v[128:129]
	global_load_lds_dwordx4 v[244:245], off
	s_add_i32 m0, s6, 0x2000
	v_lshl_add_u64 v[248:249], s[64:65], 0, v[132:133]
	global_load_lds_dwordx4 v[246:247], off
	s_mov_b32 m0, s67
	v_lshl_add_u64 v[250:251], s[64:65], 0, v[130:131]
	global_load_lds_dwordx4 v[248:249], off
	s_mov_b32 m0, s82
	s_nop 0
	global_load_lds_dwordx4 v[250:251], off
	s_waitcnt vmcnt(8)
	s_waitcnt lgkmcnt(0)
	s_barrier
; #define PG8_STAGE(bufoff, gbase, voff) do { _Pragma("unroll") for (int _i = 0; _i < 2; ++_i) \
;         __builtin_amdgcn_global_load_lds((const unsigned*)((const char*)(gbase) + (voff)[_i]), (LAS unsigned*)(lds + (bufoff) + ldsw + _i * 8192), 16, 0, 0); } while (0)
; #define PG8_LDA(dst, b, h) do { _Pragma("unroll") for (int m = 0; m < 4; ++m) _Pragma("unroll") for (int k = 0; k < 2; ++k) dst[m][k] = *(const LAS bf16x8*)(lds + PG8_SA(b, h) + aoff + m * 2048 + k * 1024); } while (0)
; #define PG8_LDB(dst, b, h) do { _Pragma("unroll") for (int n = 0; n < 2; ++n) _Pragma("unroll") for (int k = 0; k < 2; ++k) dst[n][k] = *(const LAS bf16x8*)(lds + PG8_SB(b, h) + boff + n * 2048 + k * 1024); } while (0)
; #define PG8_WAIT_V(n) asm volatile("s_waitcnt vmcnt(" #n ")" ::: "memory")
; #define PG8_WAIT_L(n) asm volatile("s_waitcnt lgkmcnt(" #n ")" ::: "memory")
; #define PG8_BAR __builtin_amdgcn_s_barrier()
; #define PG8_SCHED __builtin_amdgcn_sched_barrier(0)
; template <class Epi>
; __device__ __forceinline__ void gemm_phase(LAS unsigned char* lds, const Gemm g, const Order& S, const Epi& E) {
;     ...
;             PG8_WAIT_V(8); PG8_WAIT_L(0); PG8_BAR; PG8_MMA(1, 0, At, B0); PG8_MMA(1, 1, At, B1); PG8_BAR; PG8_SCHED;
;             PG8_LDB(B0, 1, 0); PG8_LDB(B1, 1, 1); PG8_SCHED; PG8_LDA(At, 1, 0); PG8_STAGE(PG8_SA(0, 1), a2 + hstepA, voffA);
;             PG8_WAIT_V(8); PG8_WAIT_L(0); PG8_BAR; PG8_MMA(0, 0, At, B0); PG8_MMA(0, 1, At, B1); PG8_BAR; PG8_SCHED;
	v_mfma_f32_16x16x32_bf16 v[124:127], v[146:149], v[192:195], v[124:127]
	v_mfma_f32_16x16x32_bf16 v[120:123], v[154:157], v[192:195], v[120:123]
	v_mfma_f32_16x16x32_bf16 v[116:119], v[146:149], v[218:221], v[116:119]
	v_mfma_f32_16x16x32_bf16 v[112:115], v[154:157], v[218:221], v[112:115]
	v_mfma_f32_16x16x32_bf16 v[60:63], v[146:149], v[226:229], v[60:63]
	v_mfma_f32_16x16x32_bf16 v[56:59], v[154:157], v[226:229], v[56:59]
	v_mfma_f32_16x16x32_bf16 v[52:55], v[146:149], v[234:237], v[52:55]
	v_mfma_f32_16x16x32_bf16 v[48:51], v[154:157], v[234:237], v[48:51]
	v_mfma_f32_16x16x32_bf16 v[124:127], v[150:153], v[214:217], v[124:127]
	v_mfma_f32_16x16x32_bf16 v[120:123], v[172:175], v[214:217], v[120:123]
	v_mfma_f32_16x16x32_bf16 v[116:119], v[150:153], v[222:225], v[116:119]
	v_mfma_f32_16x16x32_bf16 v[112:115], v[172:175], v[222:225], v[112:115]
	v_mfma_f32_16x16x32_bf16 v[60:63], v[150:153], v[230:233], v[60:63]
	v_mfma_f32_16x16x32_bf16 v[56:59], v[172:175], v[230:233], v[56:59]
	v_mfma_f32_16x16x32_bf16 v[52:55], v[150:153], v[238:241], v[52:55]
	v_mfma_f32_16x16x32_bf16 v[48:51], v[172:175], v[238:241], v[48:51]
	v_mfma_f32_16x16x32_bf16 v[108:111], v[176:179], v[192:195], v[108:111]
	v_mfma_f32_16x16x32_bf16 v[104:107], v[184:187], v[192:195], v[104:107]
	v_mfma_f32_16x16x32_bf16 v[100:103], v[176:179], v[218:221], v[100:103]
	v_mfma_f32_16x16x32_bf16 v[96:99], v[184:187], v[218:221], v[96:99]
	v_mfma_f32_16x16x32_bf16 v[44:47], v[176:179], v[226:229], v[44:47]
	v_mfma_f32_16x16x32_bf16 v[40:43], v[184:187], v[226:229], v[40:43]
	v_mfma_f32_16x16x32_bf16 v[36:39], v[176:179], v[234:237], v[36:39]
	v_mfma_f32_16x16x32_bf16 v[32:35], v[184:187], v[234:237], v[32:35]
	v_mfma_f32_16x16x32_bf16 v[108:111], v[180:183], v[214:217], v[108:111]
	v_mfma_f32_16x16x32_bf16 v[104:107], v[188:191], v[214:217], v[104:107]
	v_mfma_f32_16x16x32_bf16 v[100:103], v[180:183], v[222:225], v[100:103]
	v_mfma_f32_16x16x32_bf16 v[96:99], v[188:191], v[222:225], v[96:99]
	v_mfma_f32_16x16x32_bf16 v[44:47], v[180:183], v[230:233], v[44:47]
	v_mfma_f32_16x16x32_bf16 v[40:43], v[188:191], v[230:233], v[40:43]
	v_mfma_f32_16x16x32_bf16 v[36:39], v[180:183], v[238:241], v[36:39]
	v_mfma_f32_16x16x32_bf16 v[32:35], v[188:191], v[238:241], v[32:35]
	s_barrier
	s_add_i32 s6, 0, 0x18000
	s_add_i32 s7, 0, 0x1c000
	v_add_u32_e32 v172, s6, v143
	v_add_u32_e32 v188, s7, v143
	ds_read_b128 v[146:149], v172
	ds_read_b128 v[150:153], v172 offset:1024
	ds_read_b128 v[154:157], v172 offset:2048
	ds_read_b128 v[172:175], v172 offset:3072
	ds_read_b128 v[176:179], v188
	ds_read_b128 v[180:183], v188 offset:1024
	ds_read_b128 v[184:187], v188 offset:2048
	ds_read_b128 v[188:191], v188 offset:3072
	s_add_u32 s4, s64, s28
	s_addc_u32 s5, s65, 0
	s_mov_b32 m0, s46
	v_lshl_add_u64 v[200:201], s[4:5], 0, v[132:133]
	ds_read_b128 v[192:195], v144 offset:32768
	ds_read_b128 v[214:217], v144 offset:33792
	ds_read_b128 v[218:221], v144 offset:34816
	ds_read_b128 v[222:225], v144 offset:35840
	ds_read_b128 v[226:229], v144 offset:36864
	ds_read_b128 v[230:233], v144 offset:37888
	ds_read_b128 v[234:237], v144 offset:38912
	ds_read_b128 v[238:241], v144 offset:39936
	global_load_lds_dwordx4 v[200:201], off
	v_lshl_add_u64 v[200:201], s[4:5], 0, v[130:131]
	s_mov_b32 m0, s47
	s_nop 0
	global_load_lds_dwordx4 v[200:201], off
	s_waitcnt vmcnt(8)
	s_waitcnt lgkmcnt(0)
	s_barrier
	v_mfma_f32_16x16x32_bf16 v[28:31], v[146:149], v[192:195], v[28:31]
	v_mfma_f32_16x16x32_bf16 v[24:27], v[154:157], v[192:195], v[24:27]
	v_mfma_f32_16x16x32_bf16 v[20:23], v[146:149], v[218:221], v[20:23]
	v_mfma_f32_16x16x32_bf16 v[16:19], v[154:157], v[218:221], v[16:19]
	v_mfma_f32_16x16x32_bf16 v[76:79], v[146:149], v[226:229], v[76:79]
	v_mfma_f32_16x16x32_bf16 v[72:75], v[154:157], v[226:229], v[72:75]
	v_mfma_f32_16x16x32_bf16 v[92:95], v[146:149], v[234:237], v[92:95]
	v_mfma_f32_16x16x32_bf16 v[88:91], v[154:157], v[234:237], v[88:91]
	v_mfma_f32_16x16x32_bf16 v[28:31], v[150:153], v[214:217], v[28:31]
	v_mfma_f32_16x16x32_bf16 v[24:27], v[172:175], v[214:217], v[24:27]
	v_mfma_f32_16x16x32_bf16 v[20:23], v[150:153], v[222:225], v[20:23]
	v_mfma_f32_16x16x32_bf16 v[16:19], v[172:175], v[222:225], v[16:19]
	v_mfma_f32_16x16x32_bf16 v[76:79], v[150:153], v[230:233], v[76:79]
	v_mfma_f32_16x16x32_bf16 v[72:75], v[172:175], v[230:233], v[72:75]
	v_mfma_f32_16x16x32_bf16 v[92:95], v[150:153], v[238:241], v[92:95]
	v_mfma_f32_16x16x32_bf16 v[88:91], v[172:175], v[238:241], v[88:91]
	v_mfma_f32_16x16x32_bf16 v[12:15], v[176:179], v[192:195], v[12:15]
	v_mfma_f32_16x16x32_bf16 v[8:11], v[184:187], v[192:195], v[8:11]
	v_mfma_f32_16x16x32_bf16 v[4:7], v[176:179], v[218:221], v[4:7]
	v_mfma_f32_16x16x32_bf16 v[0:3], v[184:187], v[218:221], v[0:3]
	v_mfma_f32_16x16x32_bf16 v[68:71], v[176:179], v[226:229], v[68:71]
	v_mfma_f32_16x16x32_bf16 v[64:67], v[184:187], v[226:229], v[64:67]
	v_mfma_f32_16x16x32_bf16 v[84:87], v[176:179], v[234:237], v[84:87]
	v_mfma_f32_16x16x32_bf16 v[80:83], v[184:187], v[234:237], v[80:83]
	v_mfma_f32_16x16x32_bf16 v[12:15], v[180:183], v[214:217], v[12:15]
	v_mfma_f32_16x16x32_bf16 v[8:11], v[188:191], v[214:217], v[8:11]
	v_mfma_f32_16x16x32_bf16 v[4:7], v[180:183], v[222:225], v[4:7]
	v_mfma_f32_16x16x32_bf16 v[0:3], v[188:191], v[222:225], v[0:3]
	v_mfma_f32_16x16x32_bf16 v[68:71], v[180:183], v[230:233], v[68:71]
	v_mfma_f32_16x16x32_bf16 v[64:67], v[188:191], v[230:233], v[64:67]
	v_mfma_f32_16x16x32_bf16 v[84:87], v[180:183], v[238:241], v[84:87]
	v_mfma_f32_16x16x32_bf16 v[80:83], v[188:191], v[238:241], v[80:83]
	s_barrier
; #define PG8_STAGE(bufoff, gbase, voff) do { _Pragma("unroll") for (int _i = 0; _i < 2; ++_i) \
;         __builtin_amdgcn_global_load_lds((const unsigned*)((const char*)(gbase) + (voff)[_i]), (LAS unsigned*)(lds + (bufoff) + ldsw + _i * 8192), 16, 0, 0); } while (0)
; #define PG8_LDA(dst, b, h) do { _Pragma("unroll") for (int m = 0; m < 4; ++m) _Pragma("unroll") for (int k = 0; k < 2; ++k) dst[m][k] = *(const LAS bf16x8*)(lds + PG8_SA(b, h) + aoff + m * 2048 + k * 1024); } while (0)
; #define PG8_WAIT_V(n) asm volatile("s_waitcnt vmcnt(" #n ")" ::: "memory")
; #define PG8_WAIT_L(n) asm volatile("s_waitcnt lgkmcnt(" #n ")" ::: "memory")
; #define PG8_BAR __builtin_amdgcn_s_barrier()
; #define PG8_SCHED __builtin_amdgcn_sched_barrier(0)
; template <class Epi>
; __device__ __forceinline__ void gemm_phase(LAS unsigned char* lds, const Gemm g, const Order& S, const Epi& E) {
;     ...
;             PG8_LDA(At, 1, 1); PG8_STAGE(PG8_SB(1, 0), b3, voffB); PG8_STAGE(PG8_SB(1, 1), b3 + hstepB, voffB); PG8_STAGE(PG8_SA(1, 0), a3, voffA);
;             PG8_WAIT_V(8); PG8_WAIT_L(0); PG8_BAR; PG8_MMA(1, 0, At, B0); PG8_MMA(1, 1, At, B1); PG8_BAR; PG8_SCHED;
;         }
;         if constexpr (ALIGN_EPI) { if (wr == 0) PG8_BAR; }
;         if constexpr (!Epi::AFTER_DRAIN) E(acc, cur, wr, wc, fr, fq);
;         if (!has_next) break;
;         if (!(Epi::KEEP_ACC && nxt.z != 0)) {
; #pragma unroll
;         for (int a = 0; a < 2; ++a)
; #pragma unroll
;             for (int b = 0; b < 2; ++b)
; #pragma unroll
;                 for (int m = 0; m < 4; ++m)
; #pragma unroll
;                     for (int n = 0; n < 2; ++n) acc[a][b][m][n] = (f32x4){0.f, 0.f, 0.f, 0.f};
;         }
;         cur = nxt; cA = nA; cB = nB; ++ui;
;         if constexpr (ALIGN_EPI) { if (wr == 1) PG8_BAR; }
;     }
	s_add_i32 s4, s6, s29
	v_lshl_add_u64 v[158:159], v[158:159], 0, s[62:63]
	s_mov_b32 m0, s4
	ds_read_b128 v[192:195], v144 offset:49152
	ds_read_b128 v[214:217], v144 offset:50176
	ds_read_b128 v[218:221], v144 offset:51200
	ds_read_b128 v[222:225], v144 offset:52224
	ds_read_b128 v[226:229], v144 offset:53248
	ds_read_b128 v[230:233], v144 offset:54272
	ds_read_b128 v[234:237], v144 offset:55296
	ds_read_b128 v[238:241], v144 offset:56320
	global_load_lds_dwordx4 v[158:159], off
	v_lshl_add_u64 v[158:159], v[242:243], 0, s[62:63]
	s_add_i32 m0, s4, 0x2000
	s_add_i32 s4, s7, s29
	global_load_lds_dwordx4 v[158:159], off
	v_lshl_add_u64 v[158:159], v[244:245], 0, s[62:63]
	s_mov_b32 m0, s4
	s_nop 0
	global_load_lds_dwordx4 v[158:159], off
	v_lshl_add_u64 v[158:159], v[246:247], 0, s[62:63]
	s_add_i32 m0, s4, 0x2000
	s_nop 0
	global_load_lds_dwordx4 v[158:159], off
	v_lshl_add_u64 v[158:159], v[248:249], 0, s[62:63]
	s_mov_b32 m0, s50
	s_nop 0
	global_load_lds_dwordx4 v[158:159], off
	v_lshl_add_u64 v[158:159], v[250:251], 0, s[62:63]
	s_mov_b32 m0, s51
	s_nop 0
	global_load_lds_dwordx4 v[158:159], off
	s_waitcnt vmcnt(8)
	s_waitcnt lgkmcnt(0)
	s_barrier
	v_mfma_f32_16x16x32_bf16 v[124:127], v[146:149], v[192:195], v[124:127]
	v_mfma_f32_16x16x32_bf16 v[120:123], v[154:157], v[192:195], v[120:123]
	v_mfma_f32_16x16x32_bf16 v[116:119], v[146:149], v[218:221], v[116:119]
	v_mfma_f32_16x16x32_bf16 v[112:115], v[154:157], v[218:221], v[112:115]
	v_mfma_f32_16x16x32_bf16 v[60:63], v[146:149], v[226:229], v[60:63]
	v_mfma_f32_16x16x32_bf16 v[56:59], v[154:157], v[226:229], v[56:59]
	v_mfma_f32_16x16x32_bf16 v[52:55], v[146:149], v[234:237], v[52:55]
	v_mfma_f32_16x16x32_bf16 v[48:51], v[154:157], v[234:237], v[48:51]
	v_mfma_f32_16x16x32_bf16 v[124:127], v[150:153], v[214:217], v[124:127]
	v_mfma_f32_16x16x32_bf16 v[120:123], v[172:175], v[214:217], v[120:123]
	v_mfma_f32_16x16x32_bf16 v[116:119], v[150:153], v[222:225], v[116:119]
	v_mfma_f32_16x16x32_bf16 v[112:115], v[172:175], v[222:225], v[112:115]
	v_mfma_f32_16x16x32_bf16 v[60:63], v[150:153], v[230:233], v[60:63]
	v_mfma_f32_16x16x32_bf16 v[56:59], v[172:175], v[230:233], v[56:59]
	v_mfma_f32_16x16x32_bf16 v[52:55], v[150:153], v[238:241], v[52:55]
	v_mfma_f32_16x16x32_bf16 v[48:51], v[172:175], v[238:241], v[48:51]
	v_mfma_f32_16x16x32_bf16 v[108:111], v[176:179], v[192:195], v[108:111]
	v_mfma_f32_16x16x32_bf16 v[104:107], v[184:187], v[192:195], v[104:107]
	v_mfma_f32_16x16x32_bf16 v[100:103], v[176:179], v[218:221], v[100:103]
	v_mfma_f32_16x16x32_bf16 v[96:99], v[184:187], v[218:221], v[96:99]
	v_mfma_f32_16x16x32_bf16 v[44:47], v[176:179], v[226:229], v[44:47]
	v_mfma_f32_16x16x32_bf16 v[40:43], v[184:187], v[226:229], v[40:43]
	v_mfma_f32_16x16x32_bf16 v[36:39], v[176:179], v[234:237], v[36:39]
	v_mfma_f32_16x16x32_bf16 v[32:35], v[184:187], v[234:237], v[32:35]
	v_mfma_f32_16x16x32_bf16 v[108:111], v[180:183], v[214:217], v[108:111]
	v_mfma_f32_16x16x32_bf16 v[104:107], v[188:191], v[214:217], v[104:107]
	v_mfma_f32_16x16x32_bf16 v[100:103], v[180:183], v[222:225], v[100:103]
	v_mfma_f32_16x16x32_bf16 v[96:99], v[188:191], v[222:225], v[96:99]
	v_mfma_f32_16x16x32_bf16 v[44:47], v[180:183], v[230:233], v[44:47]
	v_mfma_f32_16x16x32_bf16 v[40:43], v[188:191], v[230:233], v[40:43]
	v_mfma_f32_16x16x32_bf16 v[36:39], v[180:183], v[238:241], v[36:39]
	v_mfma_f32_16x16x32_bf16 v[32:35], v[188:191], v[238:241], v[32:35]
	s_barrier
	s_add_u32 vcc_lo, vcc_lo, 0x100
	s_addc_u32 vcc_hi, vcc_hi, 0
	v_lshl_add_u64 v[140:141], v[140:141], 0, s[60:61]
	v_lshl_add_u64 v[138:139], v[138:139], 0, s[60:61]
	s_cmp_ge_u32 s36, s8
	s_mov_b32 s35, s36
	s_cbranch_scc0 .LBB0_172
	s_and_b64 vcc, exec, s[42:43]
	s_cbranch_vccnz .LBB0_160
	v_mov_b32_e32 v32, 0
	s_mov_b32 s66, s30
	s_mov_b32 s9, s31
	s_mov_b64 s[68:69], s[88:89]
	s_mov_b64 s[70:71], s[44:45]
	s_mov_b32 s34, s22
	v_mov_b32_e32 v33, v32
	v_mov_b32_e32 v34, v32
	v_mov_b32_e32 v35, v32
	v_mov_b32_e32 v36, v32
	v_mov_b32_e32 v37, v32
	v_mov_b32_e32 v38, v32
	v_mov_b32_e32 v39, v32
	v_mov_b32_e32 v40, v32
	v_mov_b32_e32 v41, v32
	v_mov_b32_e32 v42, v32
	v_mov_b32_e32 v43, v32
	v_mov_b32_e32 v44, v32
	v_mov_b32_e32 v45, v32
	v_mov_b32_e32 v46, v32
	v_mov_b32_e32 v47, v32
	v_mov_b32_e32 v96, v32
	v_mov_b32_e32 v97, v32
	v_mov_b32_e32 v98, v32
	v_mov_b32_e32 v99, v32
	v_mov_b32_e32 v100, v32
	v_mov_b32_e32 v101, v32
	v_mov_b32_e32 v102, v32
	v_mov_b32_e32 v103, v32
	v_mov_b32_e32 v104, v32
	v_mov_b32_e32 v105, v32
	v_mov_b32_e32 v106, v32
	v_mov_b32_e32 v107, v32
	v_mov_b32_e32 v108, v32
	v_mov_b32_e32 v109, v32
	v_mov_b32_e32 v110, v32
	v_mov_b32_e32 v111, v32
	v_mov_b32_e32 v48, v32
	v_mov_b32_e32 v49, v32
	v_mov_b32_e32 v50, v32
	v_mov_b32_e32 v51, v32
	v_mov_b32_e32 v52, v32
	v_mov_b32_e32 v53, v32
	v_mov_b32_e32 v54, v32
	v_mov_b32_e32 v55, v32
	v_mov_b32_e32 v56, v32
	v_mov_b32_e32 v57, v32
	v_mov_b32_e32 v58, v32
	v_mov_b32_e32 v59, v32
	v_mov_b32_e32 v60, v32
	v_mov_b32_e32 v61, v32
	v_mov_b32_e32 v62, v32
	v_mov_b32_e32 v63, v32
	v_mov_b32_e32 v112, v32
	v_mov_b32_e32 v113, v32
	v_mov_b32_e32 v114, v32
	v_mov_b32_e32 v115, v32
	v_mov_b32_e32 v116, v32
	v_mov_b32_e32 v117, v32
	v_mov_b32_e32 v118, v32
	v_mov_b32_e32 v119, v32
	v_mov_b32_e32 v120, v32
	v_mov_b32_e32 v121, v32
	v_mov_b32_e32 v122, v32
	v_mov_b32_e32 v123, v32
	v_mov_b32_e32 v124, v32
	v_mov_b32_e32 v125, v32
	v_mov_b32_e32 v126, v32
	v_mov_b32_e32 v127, v32
	v_mov_b32_e32 v80, v32
	v_mov_b32_e32 v81, v32
	v_mov_b32_e32 v82, v32
	v_mov_b32_e32 v83, v32
	v_mov_b32_e32 v84, v32
	v_mov_b32_e32 v85, v32
	v_mov_b32_e32 v86, v32
	v_mov_b32_e32 v87, v32
	v_mov_b32_e32 v64, v32
	v_mov_b32_e32 v65, v32
	v_mov_b32_e32 v66, v32
	v_mov_b32_e32 v67, v32
	v_mov_b32_e32 v68, v32
	v_mov_b32_e32 v69, v32
	v_mov_b32_e32 v70, v32
	v_mov_b32_e32 v71, v32
	v_mov_b32_e32 v0, v32
	v_mov_b32_e32 v1, v32
	v_mov_b32_e32 v2, v32
	v_mov_b32_e32 v3, v32
	v_mov_b32_e32 v4, v32
	v_mov_b32_e32 v5, v32
	v_mov_b32_e32 v6, v32
	v_mov_b32_e32 v7, v32
	v_mov_b32_e32 v8, v32
	v_mov_b32_e32 v9, v32
	v_mov_b32_e32 v10, v32
	v_mov_b32_e32 v11, v32
	v_mov_b32_e32 v12, v32
	v_mov_b32_e32 v13, v32
	v_mov_b32_e32 v14, v32
	v_mov_b32_e32 v15, v32
	v_mov_b32_e32 v88, v32
	v_mov_b32_e32 v89, v32
	v_mov_b32_e32 v90, v32
	v_mov_b32_e32 v91, v32
	v_mov_b32_e32 v92, v32
	v_mov_b32_e32 v93, v32
	v_mov_b32_e32 v94, v32
	v_mov_b32_e32 v95, v32
	v_mov_b32_e32 v72, v32
	v_mov_b32_e32 v73, v32
	v_mov_b32_e32 v74, v32
	v_mov_b32_e32 v75, v32
	v_mov_b32_e32 v76, v32
	v_mov_b32_e32 v77, v32
	v_mov_b32_e32 v78, v32
	v_mov_b32_e32 v79, v32
	v_mov_b32_e32 v16, v32
	v_mov_b32_e32 v17, v32
	v_mov_b32_e32 v18, v32
	v_mov_b32_e32 v19, v32
	v_mov_b32_e32 v20, v32
	v_mov_b32_e32 v21, v32
	v_mov_b32_e32 v22, v32
	v_mov_b32_e32 v23, v32
	v_mov_b32_e32 v24, v32
	v_mov_b32_e32 v25, v32
	v_mov_b32_e32 v26, v32
	v_mov_b32_e32 v27, v32
	v_mov_b32_e32 v28, v32
	v_mov_b32_e32 v29, v32
	v_mov_b32_e32 v30, v32
	v_mov_b32_e32 v31, v32
	s_branch .LBB0_160

; #define PG8_STAGE(bufoff, gbase, voff) do { _Pragma("unroll") for (int _i = 0; _i < 2; ++_i) \
;         __builtin_amdgcn_global_load_lds((const unsigned*)((const char*)(gbase) + (voff)[_i]), (LAS unsigned*)(lds + (bufoff) + ldsw + _i * 8192), 16, 0, 0); } while (0)
; #define PG8_LDA(dst, b, h) do { _Pragma("unroll") for (int m = 0; m < 4; ++m) _Pragma("unroll") for (int k = 0; k < 2; ++k) dst[m][k] = *(const LAS bf16x8*)(lds + PG8_SA(b, h) + aoff + m * 2048 + k * 1024); } while (0)
; #define PG8_LDB(dst, b, h) do { _Pragma("unroll") for (int n = 0; n < 2; ++n) _Pragma("unroll") for (int k = 0; k < 2; ++k) dst[n][k] = *(const LAS bf16x8*)(lds + PG8_SB(b, h) + boff + n * 2048 + k * 1024); } while (0)
; #define PG8_WAIT_V(n) asm volatile("s_waitcnt vmcnt(" #n ")" ::: "memory")
; #define PG8_WAIT_L(n) asm volatile("s_waitcnt lgkmcnt(" #n ")" ::: "memory")
; #define PG8_BAR __builtin_amdgcn_s_barrier()
; #define PG8_SCHED __builtin_amdgcn_sched_barrier(0)
; template <class Epi>
; __device__ __forceinline__ void gemm_phase(LAS unsigned char* lds, const Gemm g, const Order& S, const Epi& E) {
;     ...
;             const bool last = (t == nt - 2);
;             const char* a1 = cA + (size_t)(t + 1) * kstep;
;             const char* a2 = last ? nA : cA + (size_t)(t + 2) * kstep; const char* b2 = last ? nB : cB + (size_t)(t + 2) * kstep;
;             const char* a3 = a2 + kstep; const char* b3 = b2 + kstep;
;             PG8_LDB(B0, 0, 0); PG8_LDB(B1, 0, 1); PG8_SCHED; PG8_LDA(At, 0, 0); PG8_STAGE(PG8_SA(1, 1), a1 + hstepA, voffA);
;             PG8_WAIT_V(8); PG8_WAIT_L(0); PG8_BAR; PG8_MMA(0, 0, At, B0); PG8_MMA(0, 1, At, B1); PG8_BAR; PG8_SCHED;
;             PG8_LDA(At, 0, 1); PG8_STAGE(PG8_SB(0, 0), b2, voffB); PG8_STAGE(PG8_SB(0, 1), b2 + hstepB, voffB); PG8_STAGE(PG8_SA(0, 0), a2, voffA);
;             PG8_WAIT_V(8); PG8_WAIT_L(0); PG8_BAR; PG8_MMA(1, 0, At, B0); PG8_MMA(1, 1, At, B1); PG8_BAR; PG8_SCHED;
.LBB0_281:
	s_add_u32 s40, s64, 0x100
	s_addc_u32 s41, s65, 0
	s_add_i32 s4, 0, 0x10000
	s_cmp_eq_u32 s47, 4
	s_cselect_b32 s69, s49, s41
	s_cselect_b32 s68, s48, s40
	s_cselect_b32 s67, s34, s45
	s_cselect_b32 s66, s35, s43
	s_add_i32 s6, 0, 0x14000
	v_add_u32_e32 v150, s4, v184
	v_add_u32_e32 v158, s6, v184
	ds_read_b128 v[138:141], v150
	ds_read_b128 v[142:145], v150 offset:1024
	ds_read_b128 v[146:149], v150 offset:2048
	ds_read_b128 v[150:153], v150 offset:3072
	ds_read_b128 v[154:157], v158
	ds_read_b128 v[172:175], v158 offset:1024
	ds_read_b128 v[176:179], v158 offset:2048
	ds_read_b128 v[180:183], v158 offset:3072
	v_lshl_add_u64 v[158:159], s[64:65], 0, v[134:135]
	s_add_i32 m0, s25, 0xc000
	ds_read_b128 v[188:191], v186
	ds_read_b128 v[192:195], v186 offset:1024
	ds_read_b128 v[214:217], v186 offset:2048
	ds_read_b128 v[218:221], v186 offset:3072
	ds_read_b128 v[222:225], v186 offset:4096
	ds_read_b128 v[226:229], v186 offset:5120
	ds_read_b128 v[230:233], v186 offset:6144
	ds_read_b128 v[234:237], v186 offset:7168
	global_load_lds_dwordx4 v[158:159], off
	v_lshl_add_u64 v[158:159], s[64:65], 0, v[136:137]
	s_add_i32 m0, s25, 0xe000
	s_nop 0
	global_load_lds_dwordx4 v[158:159], off
	s_waitcnt vmcnt(8)
	s_waitcnt lgkmcnt(0)
	s_barrier
	v_mfma_f32_16x16x32_bf16 v[124:127], v[138:141], v[188:191], v[124:127]
	v_mfma_f32_16x16x32_bf16 v[120:123], v[146:149], v[188:191], v[120:123]
	v_mfma_f32_16x16x32_bf16 v[116:119], v[138:141], v[214:217], v[116:119]
	v_mfma_f32_16x16x32_bf16 v[112:115], v[146:149], v[214:217], v[112:115]
	v_mfma_f32_16x16x32_bf16 v[108:111], v[138:141], v[222:225], v[108:111]
	v_mfma_f32_16x16x32_bf16 v[104:107], v[146:149], v[222:225], v[104:107]
	v_mfma_f32_16x16x32_bf16 v[100:103], v[138:141], v[230:233], v[100:103]
	v_mfma_f32_16x16x32_bf16 v[96:99], v[146:149], v[230:233], v[96:99]
	v_mfma_f32_16x16x32_bf16 v[124:127], v[142:145], v[192:195], v[124:127]
	v_mfma_f32_16x16x32_bf16 v[120:123], v[150:153], v[192:195], v[120:123]
	v_mfma_f32_16x16x32_bf16 v[116:119], v[142:145], v[218:221], v[116:119]
	v_mfma_f32_16x16x32_bf16 v[112:115], v[150:153], v[218:221], v[112:115]
	v_mfma_f32_16x16x32_bf16 v[108:111], v[142:145], v[226:229], v[108:111]
	v_mfma_f32_16x16x32_bf16 v[104:107], v[150:153], v[226:229], v[104:107]
	v_mfma_f32_16x16x32_bf16 v[100:103], v[142:145], v[234:237], v[100:103]
	v_mfma_f32_16x16x32_bf16 v[96:99], v[150:153], v[234:237], v[96:99]
	v_mfma_f32_16x16x32_bf16 v[92:95], v[154:157], v[188:191], v[92:95]
	v_mfma_f32_16x16x32_bf16 v[88:91], v[176:179], v[188:191], v[88:91]
	v_mfma_f32_16x16x32_bf16 v[84:87], v[154:157], v[214:217], v[84:87]
	v_mfma_f32_16x16x32_bf16 v[80:83], v[176:179], v[214:217], v[80:83]
	v_mfma_f32_16x16x32_bf16 v[76:79], v[154:157], v[222:225], v[76:79]
	v_mfma_f32_16x16x32_bf16 v[72:75], v[176:179], v[222:225], v[72:75]
	v_mfma_f32_16x16x32_bf16 v[68:71], v[154:157], v[230:233], v[68:71]
	v_mfma_f32_16x16x32_bf16 v[64:67], v[176:179], v[230:233], v[64:67]
	v_mfma_f32_16x16x32_bf16 v[92:95], v[172:175], v[192:195], v[92:95]
	v_mfma_f32_16x16x32_bf16 v[88:91], v[180:183], v[192:195], v[88:91]
	v_mfma_f32_16x16x32_bf16 v[84:87], v[172:175], v[218:221], v[84:87]
	v_mfma_f32_16x16x32_bf16 v[80:83], v[180:183], v[218:221], v[80:83]
	v_mfma_f32_16x16x32_bf16 v[76:79], v[172:175], v[226:229], v[76:79]
	v_mfma_f32_16x16x32_bf16 v[72:75], v[180:183], v[226:229], v[72:75]
	v_mfma_f32_16x16x32_bf16 v[68:71], v[172:175], v[234:237], v[68:71]
	v_mfma_f32_16x16x32_bf16 v[64:67], v[180:183], v[234:237], v[64:67]
	s_barrier
	s_add_i32 s4, s4, s24
	v_lshl_add_u64 v[158:159], s[66:67], 0, v[160:161]
	s_mov_b32 m0, s4
	ds_read_b128 v[188:191], v186 offset:16384
	ds_read_b128 v[192:195], v186 offset:17408
	ds_read_b128 v[214:217], v186 offset:18432
	ds_read_b128 v[218:221], v186 offset:19456
	ds_read_b128 v[222:225], v186 offset:20480
	ds_read_b128 v[226:229], v186 offset:21504
	ds_read_b128 v[230:233], v186 offset:22528
	ds_read_b128 v[234:237], v186 offset:23552
	global_load_lds_dwordx4 v[158:159], off
	s_add_i32 m0, s4, 0x2000
	s_add_u32 s4, s66, 0x20000
	v_lshl_add_u64 v[200:201], s[66:67], 0, v[128:129]
	s_addc_u32 s5, s67, 0
	s_add_i32 s6, s6, s24
	global_load_lds_dwordx4 v[200:201], off
	v_lshl_add_u64 v[238:239], s[4:5], 0, v[160:161]
	s_mov_b32 m0, s6
	v_lshl_add_u64 v[240:241], s[68:69], 0, v[130:131]
	global_load_lds_dwordx4 v[238:239], off
	v_lshl_add_u64 v[238:239], s[4:5], 0, v[128:129]
	s_add_i32 m0, s6, 0x2000
	s_nop 0
	global_load_lds_dwordx4 v[238:239], off
	v_lshl_add_u64 v[238:239], s[68:69], 0, v[132:133]
	s_mov_b32 m0, s25
	s_nop 0
	global_load_lds_dwordx4 v[238:239], off
	s_mov_b32 m0, s26
	s_nop 0
	global_load_lds_dwordx4 v[240:241], off
	s_waitcnt vmcnt(8)
	s_waitcnt lgkmcnt(0)
	s_barrier
; #define PG8_STAGE(bufoff, gbase, voff) do { _Pragma("unroll") for (int _i = 0; _i < 2; ++_i) \
;         __builtin_amdgcn_global_load_lds((const unsigned*)((const char*)(gbase) + (voff)[_i]), (LAS unsigned*)(lds + (bufoff) + ldsw + _i * 8192), 16, 0, 0); } while (0)
; #define PG8_LDA(dst, b, h) do { _Pragma("unroll") for (int m = 0; m < 4; ++m) _Pragma("unroll") for (int k = 0; k < 2; ++k) dst[m][k] = *(const LAS bf16x8*)(lds + PG8_SA(b, h) + aoff + m * 2048 + k * 1024); } while (0)
; #define PG8_LDB(dst, b, h) do { _Pragma("unroll") for (int n = 0; n < 2; ++n) _Pragma("unroll") for (int k = 0; k < 2; ++k) dst[n][k] = *(const LAS bf16x8*)(lds + PG8_SB(b, h) + boff + n * 2048 + k * 1024); } while (0)
; #define PG8_WAIT_V(n) asm volatile("s_waitcnt vmcnt(" #n ")" ::: "memory")
; #define PG8_WAIT_L(n) asm volatile("s_waitcnt lgkmcnt(" #n ")" ::: "memory")
; #define PG8_BAR __builtin_amdgcn_s_barrier()
; #define PG8_SCHED __builtin_amdgcn_sched_barrier(0)
; template <class Epi>
; __device__ __forceinline__ void gemm_phase(LAS unsigned char* lds, const Gemm g, const Order& S, const Epi& E) {
;     ...
;             PG8_WAIT_V(8); PG8_WAIT_L(0); PG8_BAR; PG8_MMA(1, 0, At, B0); PG8_MMA(1, 1, At, B1); PG8_BAR; PG8_SCHED;
;             PG8_LDB(B0, 1, 0); PG8_LDB(B1, 1, 1); PG8_SCHED; PG8_LDA(At, 1, 0); PG8_STAGE(PG8_SA(0, 1), a2 + hstepA, voffA);
;             PG8_WAIT_V(8); PG8_WAIT_L(0); PG8_BAR; PG8_MMA(0, 0, At, B0); PG8_MMA(0, 1, At, B1); PG8_BAR; PG8_SCHED;
	v_mfma_f32_16x16x32_bf16 v[60:63], v[138:141], v[188:191], v[60:63]
	v_mfma_f32_16x16x32_bf16 v[56:59], v[146:149], v[188:191], v[56:59]
	v_mfma_f32_16x16x32_bf16 v[52:55], v[138:141], v[214:217], v[52:55]
	v_mfma_f32_16x16x32_bf16 v[48:51], v[146:149], v[214:217], v[48:51]
	v_mfma_f32_16x16x32_bf16 v[44:47], v[138:141], v[222:225], v[44:47]
	v_mfma_f32_16x16x32_bf16 v[40:43], v[146:149], v[222:225], v[40:43]
	v_mfma_f32_16x16x32_bf16 v[36:39], v[138:141], v[230:233], v[36:39]
	v_mfma_f32_16x16x32_bf16 v[32:35], v[146:149], v[230:233], v[32:35]
	v_mfma_f32_16x16x32_bf16 v[60:63], v[142:145], v[192:195], v[60:63]
	v_mfma_f32_16x16x32_bf16 v[56:59], v[150:153], v[192:195], v[56:59]
	v_mfma_f32_16x16x32_bf16 v[52:55], v[142:145], v[218:221], v[52:55]
	v_mfma_f32_16x16x32_bf16 v[48:51], v[150:153], v[218:221], v[48:51]
	v_mfma_f32_16x16x32_bf16 v[44:47], v[142:145], v[226:229], v[44:47]
	v_mfma_f32_16x16x32_bf16 v[40:43], v[150:153], v[226:229], v[40:43]
	v_mfma_f32_16x16x32_bf16 v[36:39], v[142:145], v[234:237], v[36:39]
	v_mfma_f32_16x16x32_bf16 v[32:35], v[150:153], v[234:237], v[32:35]
	v_mfma_f32_16x16x32_bf16 v[28:31], v[154:157], v[188:191], v[28:31]
	v_mfma_f32_16x16x32_bf16 v[24:27], v[176:179], v[188:191], v[24:27]
	v_mfma_f32_16x16x32_bf16 v[20:23], v[154:157], v[214:217], v[20:23]
	v_mfma_f32_16x16x32_bf16 v[16:19], v[176:179], v[214:217], v[16:19]
	v_mfma_f32_16x16x32_bf16 v[12:15], v[154:157], v[222:225], v[12:15]
	v_mfma_f32_16x16x32_bf16 v[8:11], v[176:179], v[222:225], v[8:11]
	v_mfma_f32_16x16x32_bf16 v[4:7], v[154:157], v[230:233], v[4:7]
	v_mfma_f32_16x16x32_bf16 v[0:3], v[176:179], v[230:233], v[0:3]
	v_mfma_f32_16x16x32_bf16 v[28:31], v[172:175], v[192:195], v[28:31]
	v_mfma_f32_16x16x32_bf16 v[24:27], v[180:183], v[192:195], v[24:27]
	v_mfma_f32_16x16x32_bf16 v[20:23], v[172:175], v[218:221], v[20:23]
	v_mfma_f32_16x16x32_bf16 v[16:19], v[180:183], v[218:221], v[16:19]
	v_mfma_f32_16x16x32_bf16 v[12:15], v[172:175], v[226:229], v[12:15]
	v_mfma_f32_16x16x32_bf16 v[8:11], v[180:183], v[226:229], v[8:11]
	v_mfma_f32_16x16x32_bf16 v[4:7], v[172:175], v[234:237], v[4:7]
	v_mfma_f32_16x16x32_bf16 v[0:3], v[180:183], v[234:237], v[0:3]
	s_barrier
	s_add_i32 s6, 0, 0x18000
	s_add_i32 s7, 0, 0x1c000
	v_add_u32_e32 v150, s6, v184
	v_add_u32_e32 v180, s7, v184
	ds_read_b128 v[138:141], v150
	ds_read_b128 v[142:145], v150 offset:1024
	ds_read_b128 v[146:149], v150 offset:2048
	ds_read_b128 v[150:153], v150 offset:3072
	ds_read_b128 v[154:157], v180
	ds_read_b128 v[172:175], v180 offset:1024
	ds_read_b128 v[176:179], v180 offset:2048
	ds_read_b128 v[180:183], v180 offset:3072
	s_add_u32 s4, s68, 0x60000
	s_addc_u32 s5, s69, 0
	s_mov_b32 m0, s27
	v_lshl_add_u64 v[242:243], s[4:5], 0, v[132:133]
	ds_read_b128 v[188:191], v186 offset:32768
	ds_read_b128 v[192:195], v186 offset:33792
	ds_read_b128 v[214:217], v186 offset:34816
	ds_read_b128 v[218:221], v186 offset:35840
	ds_read_b128 v[222:225], v186 offset:36864
	ds_read_b128 v[226:229], v186 offset:37888
	ds_read_b128 v[230:233], v186 offset:38912
	ds_read_b128 v[234:237], v186 offset:39936
	global_load_lds_dwordx4 v[242:243], off
	v_lshl_add_u64 v[242:243], s[4:5], 0, v[130:131]
	s_mov_b32 m0, s28
	s_nop 0
	global_load_lds_dwordx4 v[242:243], off
	s_waitcnt vmcnt(8)
	s_waitcnt lgkmcnt(0)
	s_barrier
	v_mfma_f32_16x16x32_bf16 v[124:127], v[138:141], v[188:191], v[124:127]
	v_mfma_f32_16x16x32_bf16 v[120:123], v[146:149], v[188:191], v[120:123]
	v_mfma_f32_16x16x32_bf16 v[116:119], v[138:141], v[214:217], v[116:119]
	v_mfma_f32_16x16x32_bf16 v[112:115], v[146:149], v[214:217], v[112:115]
	v_mfma_f32_16x16x32_bf16 v[108:111], v[138:141], v[222:225], v[108:111]
	v_mfma_f32_16x16x32_bf16 v[104:107], v[146:149], v[222:225], v[104:107]
	v_mfma_f32_16x16x32_bf16 v[100:103], v[138:141], v[230:233], v[100:103]
	v_mfma_f32_16x16x32_bf16 v[96:99], v[146:149], v[230:233], v[96:99]
	v_mfma_f32_16x16x32_bf16 v[124:127], v[142:145], v[192:195], v[124:127]
	v_mfma_f32_16x16x32_bf16 v[120:123], v[150:153], v[192:195], v[120:123]
	v_mfma_f32_16x16x32_bf16 v[116:119], v[142:145], v[218:221], v[116:119]
	v_mfma_f32_16x16x32_bf16 v[112:115], v[150:153], v[218:221], v[112:115]
	v_mfma_f32_16x16x32_bf16 v[108:111], v[142:145], v[226:229], v[108:111]
	v_mfma_f32_16x16x32_bf16 v[104:107], v[150:153], v[226:229], v[104:107]
	v_mfma_f32_16x16x32_bf16 v[100:103], v[142:145], v[234:237], v[100:103]
	v_mfma_f32_16x16x32_bf16 v[96:99], v[150:153], v[234:237], v[96:99]
	v_mfma_f32_16x16x32_bf16 v[92:95], v[154:157], v[188:191], v[92:95]
	v_mfma_f32_16x16x32_bf16 v[88:91], v[176:179], v[188:191], v[88:91]
	v_mfma_f32_16x16x32_bf16 v[84:87], v[154:157], v[214:217], v[84:87]
	v_mfma_f32_16x16x32_bf16 v[80:83], v[176:179], v[214:217], v[80:83]
	v_mfma_f32_16x16x32_bf16 v[76:79], v[154:157], v[222:225], v[76:79]
	v_mfma_f32_16x16x32_bf16 v[72:75], v[176:179], v[222:225], v[72:75]
	v_mfma_f32_16x16x32_bf16 v[68:71], v[154:157], v[230:233], v[68:71]
	v_mfma_f32_16x16x32_bf16 v[64:67], v[176:179], v[230:233], v[64:67]
	v_mfma_f32_16x16x32_bf16 v[92:95], v[172:175], v[192:195], v[92:95]
	v_mfma_f32_16x16x32_bf16 v[88:91], v[180:183], v[192:195], v[88:91]
	v_mfma_f32_16x16x32_bf16 v[84:87], v[172:175], v[218:221], v[84:87]
	v_mfma_f32_16x16x32_bf16 v[80:83], v[180:183], v[218:221], v[80:83]
	v_mfma_f32_16x16x32_bf16 v[76:79], v[172:175], v[226:229], v[76:79]
	v_mfma_f32_16x16x32_bf16 v[72:75], v[180:183], v[226:229], v[72:75]
	v_mfma_f32_16x16x32_bf16 v[68:71], v[172:175], v[234:237], v[68:71]
	v_mfma_f32_16x16x32_bf16 v[64:67], v[180:183], v[234:237], v[64:67]
	s_barrier
; #define PG8_STAGE(bufoff, gbase, voff) do { _Pragma("unroll") for (int _i = 0; _i < 2; ++_i) \
;         __builtin_amdgcn_global_load_lds((const unsigned*)((const char*)(gbase) + (voff)[_i]), (LAS unsigned*)(lds + (bufoff) + ldsw + _i * 8192), 16, 0, 0); } while (0)
; #define PG8_LDA(dst, b, h) do { _Pragma("unroll") for (int m = 0; m < 4; ++m) _Pragma("unroll") for (int k = 0; k < 2; ++k) dst[m][k] = *(const LAS bf16x8*)(lds + PG8_SA(b, h) + aoff + m * 2048 + k * 1024); } while (0)
; #define PG8_WAIT_V(n) asm volatile("s_waitcnt vmcnt(" #n ")" ::: "memory")
; #define PG8_WAIT_L(n) asm volatile("s_waitcnt lgkmcnt(" #n ")" ::: "memory")
; #define PG8_BAR __builtin_amdgcn_s_barrier()
; #define PG8_SCHED __builtin_amdgcn_sched_barrier(0)
; template <class Epi>
; __device__ __forceinline__ void gemm_phase(LAS unsigned char* lds, const Gemm g, const Order& S, const Epi& E) {
;     ...
;             PG8_LDA(At, 1, 1); PG8_STAGE(PG8_SB(1, 0), b3, voffB); PG8_STAGE(PG8_SB(1, 1), b3 + hstepB, voffB); PG8_STAGE(PG8_SA(1, 0), a3, voffA);
;             PG8_WAIT_V(8); PG8_WAIT_L(0); PG8_BAR; PG8_MMA(1, 0, At, B0); PG8_MMA(1, 1, At, B1); PG8_BAR; PG8_SCHED;
;         }
;         if constexpr (ALIGN_EPI) { if (wr == 0) PG8_BAR; }
;         if constexpr (!Epi::AFTER_DRAIN) E(acc, cur, wr, wc, fr, fq);
;         if (!has_next) break;
	s_add_i32 s4, s6, s24
	v_lshl_add_u64 v[158:159], v[158:159], 0, s[62:63]
	s_mov_b32 m0, s4
	ds_read_b128 v[188:191], v186 offset:49152
	ds_read_b128 v[192:195], v186 offset:50176
	ds_read_b128 v[214:217], v186 offset:51200
	ds_read_b128 v[218:221], v186 offset:52224
	ds_read_b128 v[222:225], v186 offset:53248
	ds_read_b128 v[226:229], v186 offset:54272
	ds_read_b128 v[230:233], v186 offset:55296
	ds_read_b128 v[234:237], v186 offset:56320
	global_load_lds_dwordx4 v[158:159], off
	s_add_i32 m0, s4, 0x2000
	s_add_u32 s4, s66, 0x20080
	v_lshl_add_u64 v[158:159], v[200:201], 0, s[62:63]
	s_addc_u32 s5, s67, 0
	s_add_i32 s6, s7, s24
	global_load_lds_dwordx4 v[158:159], off
	v_lshl_add_u64 v[158:159], s[4:5], 0, v[160:161]
	s_mov_b32 m0, s6
	s_nop 0
	global_load_lds_dwordx4 v[158:159], off
	v_lshl_add_u64 v[158:159], s[4:5], 0, v[128:129]
	s_add_i32 m0, s6, 0x2000
	s_nop 0
	global_load_lds_dwordx4 v[158:159], off
	v_lshl_add_u64 v[158:159], v[238:239], 0, s[62:63]
	s_mov_b32 m0, s29
	s_nop 0
	global_load_lds_dwordx4 v[158:159], off
	v_lshl_add_u64 v[158:159], v[240:241], 0, s[62:63]
	s_mov_b32 m0, s70
	s_nop 0
	global_load_lds_dwordx4 v[158:159], off
	s_waitcnt vmcnt(8)
	s_waitcnt lgkmcnt(0)
	s_barrier
	v_mfma_f32_16x16x32_bf16 v[60:63], v[138:141], v[188:191], v[60:63]
	v_mfma_f32_16x16x32_bf16 v[56:59], v[146:149], v[188:191], v[56:59]
	v_mfma_f32_16x16x32_bf16 v[52:55], v[138:141], v[214:217], v[52:55]
	v_mfma_f32_16x16x32_bf16 v[48:51], v[146:149], v[214:217], v[48:51]
	v_mfma_f32_16x16x32_bf16 v[44:47], v[138:141], v[222:225], v[44:47]
	v_mfma_f32_16x16x32_bf16 v[40:43], v[146:149], v[222:225], v[40:43]
	v_mfma_f32_16x16x32_bf16 v[36:39], v[138:141], v[230:233], v[36:39]
	v_mfma_f32_16x16x32_bf16 v[32:35], v[146:149], v[230:233], v[32:35]
	v_mfma_f32_16x16x32_bf16 v[60:63], v[142:145], v[192:195], v[60:63]
	v_mfma_f32_16x16x32_bf16 v[56:59], v[150:153], v[192:195], v[56:59]
	v_mfma_f32_16x16x32_bf16 v[52:55], v[142:145], v[218:221], v[52:55]
	v_mfma_f32_16x16x32_bf16 v[48:51], v[150:153], v[218:221], v[48:51]
	v_mfma_f32_16x16x32_bf16 v[44:47], v[142:145], v[226:229], v[44:47]
	v_mfma_f32_16x16x32_bf16 v[40:43], v[150:153], v[226:229], v[40:43]
	v_mfma_f32_16x16x32_bf16 v[36:39], v[142:145], v[234:237], v[36:39]
	v_mfma_f32_16x16x32_bf16 v[32:35], v[150:153], v[234:237], v[32:35]
	v_mfma_f32_16x16x32_bf16 v[28:31], v[154:157], v[188:191], v[28:31]
	v_mfma_f32_16x16x32_bf16 v[24:27], v[176:179], v[188:191], v[24:27]
	v_mfma_f32_16x16x32_bf16 v[20:23], v[154:157], v[214:217], v[20:23]
	v_mfma_f32_16x16x32_bf16 v[16:19], v[176:179], v[214:217], v[16:19]
	v_mfma_f32_16x16x32_bf16 v[12:15], v[154:157], v[222:225], v[12:15]
	v_mfma_f32_16x16x32_bf16 v[8:11], v[176:179], v[222:225], v[8:11]
	v_mfma_f32_16x16x32_bf16 v[4:7], v[154:157], v[230:233], v[4:7]
	v_mfma_f32_16x16x32_bf16 v[0:3], v[176:179], v[230:233], v[0:3]
	v_mfma_f32_16x16x32_bf16 v[28:31], v[172:175], v[192:195], v[28:31]
	v_mfma_f32_16x16x32_bf16 v[24:27], v[180:183], v[192:195], v[24:27]
	v_mfma_f32_16x16x32_bf16 v[20:23], v[172:175], v[218:221], v[20:23]
	v_mfma_f32_16x16x32_bf16 v[16:19], v[180:183], v[218:221], v[16:19]
	v_mfma_f32_16x16x32_bf16 v[12:15], v[172:175], v[226:229], v[12:15]
	v_mfma_f32_16x16x32_bf16 v[8:11], v[180:183], v[226:229], v[8:11]
	v_mfma_f32_16x16x32_bf16 v[4:7], v[172:175], v[234:237], v[4:7]
	v_mfma_f32_16x16x32_bf16 v[0:3], v[180:183], v[234:237], v[0:3]
	s_barrier
	s_add_i32 s47, s47, 2
	s_add_u32 s43, s43, 0x100
	s_addc_u32 s45, s45, 0
	s_cmp_gt_u32 s47, 5
	s_mov_b64 s[64:65], s[40:41]
	s_cbranch_scc0 .LBB0_281
	s_and_b64 vcc, exec, s[12:13]
	s_cbranch_vccz .LBB0_284
	s_barrier

; #define PG8_STAGE(bufoff, gbase, voff) do { _Pragma("unroll") for (int _i = 0; _i < 2; ++_i) \
;         __builtin_amdgcn_global_load_lds((const unsigned*)((const char*)(gbase) + (voff)[_i]), (LAS unsigned*)(lds + (bufoff) + ldsw + _i * 8192), 16, 0, 0); } while (0)
; #define PG8_LDA(dst, b, h) do { _Pragma("unroll") for (int m = 0; m < 4; ++m) _Pragma("unroll") for (int k = 0; k < 2; ++k) dst[m][k] = *(const LAS bf16x8*)(lds + PG8_SA(b, h) + aoff + m * 2048 + k * 1024); } while (0)
; #define PG8_LDB(dst, b, h) do { _Pragma("unroll") for (int n = 0; n < 2; ++n) _Pragma("unroll") for (int k = 0; k < 2; ++k) dst[n][k] = *(const LAS bf16x8*)(lds + PG8_SB(b, h) + boff + n * 2048 + k * 1024); } while (0)
; #define PG8_WAIT_V(n) asm volatile("s_waitcnt vmcnt(" #n ")" ::: "memory")
; #define PG8_WAIT_L(n) asm volatile("s_waitcnt lgkmcnt(" #n ")" ::: "memory")
; #define PG8_BAR __builtin_amdgcn_s_barrier()
; #define PG8_SCHED __builtin_amdgcn_sched_barrier(0)
; template <class Epi>
; __device__ __forceinline__ void gemm_phase(LAS unsigned char* lds, const Gemm g, const Order& S, const Epi& E) {
;     ...
;             const bool last = (t == nt - 2);
;             const char* a1 = cA + (size_t)(t + 1) * kstep;
;             const char* a2 = last ? nA : cA + (size_t)(t + 2) * kstep; const char* b2 = last ? nB : cB + (size_t)(t + 2) * kstep;
;             const char* a3 = a2 + kstep; const char* b3 = b2 + kstep;
;             PG8_LDB(B0, 0, 0); PG8_LDB(B1, 0, 1); PG8_SCHED; PG8_LDA(At, 0, 0); PG8_STAGE(PG8_SA(1, 1), a1 + hstepA, voffA);
;             PG8_WAIT_V(8); PG8_WAIT_L(0); PG8_BAR; PG8_MMA(0, 0, At, B0); PG8_MMA(0, 1, At, B1); PG8_BAR; PG8_SCHED;
;             PG8_LDA(At, 0, 1); PG8_STAGE(PG8_SB(0, 0), b2, voffB); PG8_STAGE(PG8_SB(0, 1), b2 + hstepB, voffB); PG8_STAGE(PG8_SA(0, 0), a2, voffA);
;             PG8_WAIT_V(8); PG8_WAIT_L(0); PG8_BAR; PG8_MMA(1, 0, At, B0); PG8_MMA(1, 1, At, B1); PG8_BAR; PG8_SCHED;
.LBB0_396:
	s_add_u32 s4, s50, 0xfffc0080
	s_addc_u32 s5, s51, -1
	s_add_i32 s36, 0, 0x10000
	s_cmp_eq_u32 s71, 12
	s_cselect_b32 s67, s34, s5
	s_cselect_b32 s66, s35, s4
	v_add_u32_e32 v138, s36, v141
	s_cselect_b32 s65, s43, s70
	s_cselect_b32 s64, s45, s69
	s_add_i32 s4, 0, 0x14000
	ds_read_b128 v[144:147], v138
	ds_read_b128 v[148:151], v138 offset:1024
	ds_read_b128 v[152:155], v138 offset:2048
	ds_read_b128 v[156:159], v138 offset:3072
	v_add_u32_e32 v138, s4, v141
	ds_read_b128 v[172:175], v138
	ds_read_b128 v[176:179], v138 offset:1024
	ds_read_b128 v[180:183], v138 offset:2048
	ds_read_b128 v[184:187], v138 offset:3072
	v_lshl_add_u64 v[138:139], s[50:51], 0, v[134:135]
	s_add_i32 m0, s24, 0xc000
	ds_read_b128 v[188:191], v143
	ds_read_b128 v[192:195], v143 offset:1024
	ds_read_b128 v[214:217], v143 offset:2048
	ds_read_b128 v[218:221], v143 offset:3072
	ds_read_b128 v[222:225], v143 offset:4096
	ds_read_b128 v[226:229], v143 offset:5120
	ds_read_b128 v[230:233], v143 offset:6144
	ds_read_b128 v[234:237], v143 offset:7168
	global_load_lds_dwordx4 v[138:139], off
	v_lshl_add_u64 v[138:139], s[50:51], 0, v[136:137]
	s_add_i32 m0, s24, 0xe000
	s_nop 0
	global_load_lds_dwordx4 v[138:139], off
	s_waitcnt vmcnt(8)
	s_waitcnt lgkmcnt(0)
	s_barrier
	v_mfma_f32_16x16x32_f16 v[124:127], v[144:147], v[188:191], v[124:127]
	v_mfma_f32_16x16x32_f16 v[112:115], v[152:155], v[188:191], v[112:115]
	v_mfma_f32_16x16x32_f16 v[108:111], v[144:147], v[214:217], v[108:111]
	v_mfma_f32_16x16x32_f16 v[96:99], v[152:155], v[214:217], v[96:99]
	v_mfma_f32_16x16x32_f16 v[92:95], v[144:147], v[222:225], v[92:95]
	v_mfma_f32_16x16x32_f16 v[80:83], v[152:155], v[222:225], v[80:83]
	v_mfma_f32_16x16x32_f16 v[76:79], v[144:147], v[230:233], v[76:79]
	v_mfma_f32_16x16x32_f16 v[64:67], v[152:155], v[230:233], v[64:67]
	v_mfma_f32_16x16x32_f16 v[124:127], v[148:151], v[192:195], v[124:127]
	v_mfma_f32_16x16x32_f16 v[112:115], v[156:159], v[192:195], v[112:115]
	v_mfma_f32_16x16x32_f16 v[108:111], v[148:151], v[218:221], v[108:111]
	v_mfma_f32_16x16x32_f16 v[96:99], v[156:159], v[218:221], v[96:99]
	v_mfma_f32_16x16x32_f16 v[92:95], v[148:151], v[226:229], v[92:95]
	v_mfma_f32_16x16x32_f16 v[80:83], v[156:159], v[226:229], v[80:83]
	v_mfma_f32_16x16x32_f16 v[76:79], v[148:151], v[234:237], v[76:79]
	v_mfma_f32_16x16x32_f16 v[64:67], v[156:159], v[234:237], v[64:67]
	v_mfma_f32_16x16x32_f16 v[120:123], v[172:175], v[188:191], v[120:123]
	v_mfma_f32_16x16x32_f16 v[116:119], v[180:183], v[188:191], v[116:119]
	v_mfma_f32_16x16x32_f16 v[104:107], v[172:175], v[214:217], v[104:107]
	v_mfma_f32_16x16x32_f16 v[100:103], v[180:183], v[214:217], v[100:103]
	v_mfma_f32_16x16x32_f16 v[88:91], v[172:175], v[222:225], v[88:91]
	v_mfma_f32_16x16x32_f16 v[84:87], v[180:183], v[222:225], v[84:87]
	v_mfma_f32_16x16x32_f16 v[72:75], v[172:175], v[230:233], v[72:75]
	v_mfma_f32_16x16x32_f16 v[68:71], v[180:183], v[230:233], v[68:71]
	v_mfma_f32_16x16x32_f16 v[120:123], v[176:179], v[192:195], v[120:123]
	v_mfma_f32_16x16x32_f16 v[116:119], v[184:187], v[192:195], v[116:119]
	v_mfma_f32_16x16x32_f16 v[104:107], v[176:179], v[218:221], v[104:107]
	v_mfma_f32_16x16x32_f16 v[100:103], v[184:187], v[218:221], v[100:103]
	v_mfma_f32_16x16x32_f16 v[88:91], v[176:179], v[226:229], v[88:91]
	v_mfma_f32_16x16x32_f16 v[84:87], v[184:187], v[226:229], v[84:87]
	v_mfma_f32_16x16x32_f16 v[72:75], v[176:179], v[234:237], v[72:75]
	v_mfma_f32_16x16x32_f16 v[68:71], v[184:187], v[234:237], v[68:71]
	s_barrier
	s_add_i32 s5, s36, s23
	v_lshl_add_u64 v[138:139], s[64:65], 0, v[160:161]
	s_mov_b32 m0, s5
	ds_read_b128 v[188:191], v143 offset:16384
	ds_read_b128 v[192:195], v143 offset:17408
	ds_read_b128 v[214:217], v143 offset:18432
	ds_read_b128 v[218:221], v143 offset:19456
	ds_read_b128 v[222:225], v143 offset:20480
	ds_read_b128 v[226:229], v143 offset:21504
	ds_read_b128 v[230:233], v143 offset:22528
	ds_read_b128 v[234:237], v143 offset:23552
	global_load_lds_dwordx4 v[138:139], off
	s_add_i32 m0, s5, 0x2000
	s_add_u32 s36, s64, 0x40000
	v_lshl_add_u64 v[238:239], s[64:65], 0, v[128:129]
	s_addc_u32 s37, s65, 0
	s_add_i32 s4, s4, s23
	global_load_lds_dwordx4 v[238:239], off
	v_lshl_add_u64 v[240:241], s[36:37], 0, v[160:161]
	s_mov_b32 m0, s4
	v_lshl_add_u64 v[242:243], s[66:67], 0, v[130:131]
	global_load_lds_dwordx4 v[240:241], off
	v_lshl_add_u64 v[240:241], s[36:37], 0, v[128:129]
	s_add_i32 m0, s4, 0x2000
	s_nop 0
	global_load_lds_dwordx4 v[240:241], off
	v_lshl_add_u64 v[240:241], s[66:67], 0, v[132:133]
	s_mov_b32 m0, s24
	s_nop 0
	global_load_lds_dwordx4 v[240:241], off
	s_mov_b32 m0, s25
	s_nop 0
	global_load_lds_dwordx4 v[242:243], off
	s_waitcnt vmcnt(8)
	s_waitcnt lgkmcnt(0)
	s_barrier
; #define PG8_STAGE(bufoff, gbase, voff) do { _Pragma("unroll") for (int _i = 0; _i < 2; ++_i) \
;         __builtin_amdgcn_global_load_lds((const unsigned*)((const char*)(gbase) + (voff)[_i]), (LAS unsigned*)(lds + (bufoff) + ldsw + _i * 8192), 16, 0, 0); } while (0)
; #define PG8_LDA(dst, b, h) do { _Pragma("unroll") for (int m = 0; m < 4; ++m) _Pragma("unroll") for (int k = 0; k < 2; ++k) dst[m][k] = *(const LAS bf16x8*)(lds + PG8_SA(b, h) + aoff + m * 2048 + k * 1024); } while (0)
; #define PG8_LDB(dst, b, h) do { _Pragma("unroll") for (int n = 0; n < 2; ++n) _Pragma("unroll") for (int k = 0; k < 2; ++k) dst[n][k] = *(const LAS bf16x8*)(lds + PG8_SB(b, h) + boff + n * 2048 + k * 1024); } while (0)
; #define PG8_WAIT_V(n) asm volatile("s_waitcnt vmcnt(" #n ")" ::: "memory")
; #define PG8_WAIT_L(n) asm volatile("s_waitcnt lgkmcnt(" #n ")" ::: "memory")
; #define PG8_BAR __builtin_amdgcn_s_barrier()
; #define PG8_SCHED __builtin_amdgcn_sched_barrier(0)
; template <class Epi>
; __device__ __forceinline__ void gemm_phase(LAS unsigned char* lds, const Gemm g, const Order& S, const Epi& E) {
;     ...
;             PG8_WAIT_V(8); PG8_WAIT_L(0); PG8_BAR; PG8_MMA(1, 0, At, B0); PG8_MMA(1, 1, At, B1); PG8_BAR; PG8_SCHED;
;             PG8_LDB(B0, 1, 0); PG8_LDB(B1, 1, 1); PG8_SCHED; PG8_LDA(At, 1, 0); PG8_STAGE(PG8_SA(0, 1), a2 + hstepA, voffA);
;             PG8_WAIT_V(8); PG8_WAIT_L(0); PG8_BAR; PG8_MMA(0, 0, At, B0); PG8_MMA(0, 1, At, B1); PG8_BAR; PG8_SCHED;
	v_mfma_f32_16x16x32_f16 v[60:63], v[144:147], v[188:191], v[60:63]
	v_mfma_f32_16x16x32_f16 v[48:51], v[152:155], v[188:191], v[48:51]
	v_mfma_f32_16x16x32_f16 v[44:47], v[144:147], v[214:217], v[44:47]
	v_mfma_f32_16x16x32_f16 v[32:35], v[152:155], v[214:217], v[32:35]
	v_mfma_f32_16x16x32_f16 v[28:31], v[144:147], v[222:225], v[28:31]
	v_mfma_f32_16x16x32_f16 v[16:19], v[152:155], v[222:225], v[16:19]
	v_mfma_f32_16x16x32_f16 v[12:15], v[144:147], v[230:233], v[12:15]
	v_mfma_f32_16x16x32_f16 v[0:3], v[152:155], v[230:233], v[0:3]
	v_mfma_f32_16x16x32_f16 v[60:63], v[148:151], v[192:195], v[60:63]
	v_mfma_f32_16x16x32_f16 v[48:51], v[156:159], v[192:195], v[48:51]
	v_mfma_f32_16x16x32_f16 v[44:47], v[148:151], v[218:221], v[44:47]
	v_mfma_f32_16x16x32_f16 v[32:35], v[156:159], v[218:221], v[32:35]
	v_mfma_f32_16x16x32_f16 v[28:31], v[148:151], v[226:229], v[28:31]
	v_mfma_f32_16x16x32_f16 v[16:19], v[156:159], v[226:229], v[16:19]
	v_mfma_f32_16x16x32_f16 v[12:15], v[148:151], v[234:237], v[12:15]
	v_mfma_f32_16x16x32_f16 v[0:3], v[156:159], v[234:237], v[0:3]
	v_mfma_f32_16x16x32_f16 v[56:59], v[172:175], v[188:191], v[56:59]
	v_mfma_f32_16x16x32_f16 v[52:55], v[180:183], v[188:191], v[52:55]
	v_mfma_f32_16x16x32_f16 v[40:43], v[172:175], v[214:217], v[40:43]
	v_mfma_f32_16x16x32_f16 v[36:39], v[180:183], v[214:217], v[36:39]
	v_mfma_f32_16x16x32_f16 v[24:27], v[172:175], v[222:225], v[24:27]
	v_mfma_f32_16x16x32_f16 v[20:23], v[180:183], v[222:225], v[20:23]
	v_mfma_f32_16x16x32_f16 v[8:11], v[172:175], v[230:233], v[8:11]
	v_mfma_f32_16x16x32_f16 v[4:7], v[180:183], v[230:233], v[4:7]
	v_mfma_f32_16x16x32_f16 v[56:59], v[176:179], v[192:195], v[56:59]
	v_mfma_f32_16x16x32_f16 v[52:55], v[184:187], v[192:195], v[52:55]
	v_mfma_f32_16x16x32_f16 v[40:43], v[176:179], v[218:221], v[40:43]
	v_mfma_f32_16x16x32_f16 v[36:39], v[184:187], v[218:221], v[36:39]
	v_mfma_f32_16x16x32_f16 v[24:27], v[176:179], v[226:229], v[24:27]
	v_mfma_f32_16x16x32_f16 v[20:23], v[184:187], v[226:229], v[20:23]
	v_mfma_f32_16x16x32_f16 v[8:11], v[176:179], v[234:237], v[8:11]
	v_mfma_f32_16x16x32_f16 v[4:7], v[184:187], v[234:237], v[4:7]
	s_barrier
	s_add_i32 s4, 0, 0x18000
	s_add_i32 s5, 0, 0x1c000
	v_add_u32_e32 v156, s4, v141
	v_add_u32_e32 v171, s5, v141
	ds_read_b128 v[144:147], v156
	ds_read_b128 v[148:151], v156 offset:1024
	ds_read_b128 v[152:155], v156 offset:2048
	ds_read_b128 v[156:159], v156 offset:3072
	ds_read_b128 v[172:175], v171
	ds_read_b128 v[176:179], v171 offset:1024
	ds_read_b128 v[180:183], v171 offset:2048
	ds_read_b128 v[184:187], v171 offset:3072
	s_add_u32 s36, s66, 0x40000
	s_addc_u32 s37, s67, 0
	s_mov_b32 m0, s26
	v_lshl_add_u64 v[244:245], s[36:37], 0, v[132:133]
	ds_read_b128 v[188:191], v143 offset:32768
	ds_read_b128 v[192:195], v143 offset:33792
	ds_read_b128 v[214:217], v143 offset:34816
	ds_read_b128 v[218:221], v143 offset:35840
	ds_read_b128 v[222:225], v143 offset:36864
	ds_read_b128 v[226:229], v143 offset:37888
	ds_read_b128 v[230:233], v143 offset:38912
	ds_read_b128 v[234:237], v143 offset:39936
	global_load_lds_dwordx4 v[244:245], off
	v_lshl_add_u64 v[244:245], s[36:37], 0, v[130:131]
	s_mov_b32 m0, s27
	s_nop 0
	global_load_lds_dwordx4 v[244:245], off
	s_waitcnt vmcnt(8)
	s_waitcnt lgkmcnt(0)
	s_barrier
	v_mfma_f32_16x16x32_f16 v[124:127], v[144:147], v[188:191], v[124:127]
	v_mfma_f32_16x16x32_f16 v[112:115], v[152:155], v[188:191], v[112:115]
	v_mfma_f32_16x16x32_f16 v[108:111], v[144:147], v[214:217], v[108:111]
	v_mfma_f32_16x16x32_f16 v[96:99], v[152:155], v[214:217], v[96:99]
	v_mfma_f32_16x16x32_f16 v[92:95], v[144:147], v[222:225], v[92:95]
	v_mfma_f32_16x16x32_f16 v[80:83], v[152:155], v[222:225], v[80:83]
	v_mfma_f32_16x16x32_f16 v[76:79], v[144:147], v[230:233], v[76:79]
	v_mfma_f32_16x16x32_f16 v[64:67], v[152:155], v[230:233], v[64:67]
	v_mfma_f32_16x16x32_f16 v[124:127], v[148:151], v[192:195], v[124:127]
	v_mfma_f32_16x16x32_f16 v[112:115], v[156:159], v[192:195], v[112:115]
	v_mfma_f32_16x16x32_f16 v[108:111], v[148:151], v[218:221], v[108:111]
	v_mfma_f32_16x16x32_f16 v[96:99], v[156:159], v[218:221], v[96:99]
	v_mfma_f32_16x16x32_f16 v[92:95], v[148:151], v[226:229], v[92:95]
	v_mfma_f32_16x16x32_f16 v[80:83], v[156:159], v[226:229], v[80:83]
	v_mfma_f32_16x16x32_f16 v[76:79], v[148:151], v[234:237], v[76:79]
	v_mfma_f32_16x16x32_f16 v[64:67], v[156:159], v[234:237], v[64:67]
	v_mfma_f32_16x16x32_f16 v[120:123], v[172:175], v[188:191], v[120:123]
	v_mfma_f32_16x16x32_f16 v[116:119], v[180:183], v[188:191], v[116:119]
	v_mfma_f32_16x16x32_f16 v[104:107], v[172:175], v[214:217], v[104:107]
	v_mfma_f32_16x16x32_f16 v[100:103], v[180:183], v[214:217], v[100:103]
	v_mfma_f32_16x16x32_f16 v[88:91], v[172:175], v[222:225], v[88:91]
	v_mfma_f32_16x16x32_f16 v[84:87], v[180:183], v[222:225], v[84:87]
	v_mfma_f32_16x16x32_f16 v[72:75], v[172:175], v[230:233], v[72:75]
	v_mfma_f32_16x16x32_f16 v[68:71], v[180:183], v[230:233], v[68:71]
	v_mfma_f32_16x16x32_f16 v[120:123], v[176:179], v[192:195], v[120:123]
	v_mfma_f32_16x16x32_f16 v[116:119], v[184:187], v[192:195], v[116:119]
	v_mfma_f32_16x16x32_f16 v[104:107], v[176:179], v[218:221], v[104:107]
	v_mfma_f32_16x16x32_f16 v[100:103], v[184:187], v[218:221], v[100:103]
	v_mfma_f32_16x16x32_f16 v[88:91], v[176:179], v[226:229], v[88:91]
	v_mfma_f32_16x16x32_f16 v[84:87], v[184:187], v[226:229], v[84:87]
	v_mfma_f32_16x16x32_f16 v[72:75], v[176:179], v[234:237], v[72:75]
	v_mfma_f32_16x16x32_f16 v[68:71], v[184:187], v[234:237], v[68:71]
	s_barrier
; #define PG8_STAGE(bufoff, gbase, voff) do { _Pragma("unroll") for (int _i = 0; _i < 2; ++_i) \
;         __builtin_amdgcn_global_load_lds((const unsigned*)((const char*)(gbase) + (voff)[_i]), (LAS unsigned*)(lds + (bufoff) + ldsw + _i * 8192), 16, 0, 0); } while (0)
; #define PG8_LDA(dst, b, h) do { _Pragma("unroll") for (int m = 0; m < 4; ++m) _Pragma("unroll") for (int k = 0; k < 2; ++k) dst[m][k] = *(const LAS bf16x8*)(lds + PG8_SA(b, h) + aoff + m * 2048 + k * 1024); } while (0)
; #define PG8_WAIT_V(n) asm volatile("s_waitcnt vmcnt(" #n ")" ::: "memory")
; #define PG8_WAIT_L(n) asm volatile("s_waitcnt lgkmcnt(" #n ")" ::: "memory")
; #define PG8_BAR __builtin_amdgcn_s_barrier()
; #define PG8_SCHED __builtin_amdgcn_sched_barrier(0)
; template <class Epi>
; __device__ __forceinline__ void gemm_phase(LAS unsigned char* lds, const Gemm g, const Order& S, const Epi& E) {
;     ...
;             PG8_LDA(At, 1, 1); PG8_STAGE(PG8_SB(1, 0), b3, voffB); PG8_STAGE(PG8_SB(1, 1), b3 + hstepB, voffB); PG8_STAGE(PG8_SA(1, 0), a3, voffA);
;             PG8_WAIT_V(8); PG8_WAIT_L(0); PG8_BAR; PG8_MMA(1, 0, At, B0); PG8_MMA(1, 1, At, B1); PG8_BAR; PG8_SCHED;
;         }
;         if constexpr (ALIGN_EPI) { if (wr == 0) PG8_BAR; }
;         if constexpr (!Epi::AFTER_DRAIN) E(acc, cur, wr, wc, fr, fq);
;         if (!has_next) break;
	s_add_i32 s4, s4, s23
	v_lshl_add_u64 v[138:139], v[138:139], 0, s[62:63]
	s_mov_b32 m0, s4
	ds_read_b128 v[188:191], v143 offset:49152
	ds_read_b128 v[192:195], v143 offset:50176
	ds_read_b128 v[214:217], v143 offset:51200
	ds_read_b128 v[218:221], v143 offset:52224
	ds_read_b128 v[222:225], v143 offset:53248
	ds_read_b128 v[226:229], v143 offset:54272
	ds_read_b128 v[230:233], v143 offset:55296
	ds_read_b128 v[234:237], v143 offset:56320
	global_load_lds_dwordx4 v[138:139], off
	s_add_i32 m0, s4, 0x2000
	s_add_u32 s36, s64, 0x40080
	v_lshl_add_u64 v[138:139], v[238:239], 0, s[62:63]
	s_addc_u32 s37, s65, 0
	s_add_i32 s4, s5, s23
	global_load_lds_dwordx4 v[138:139], off
	v_lshl_add_u64 v[138:139], s[36:37], 0, v[160:161]
	s_mov_b32 m0, s4
	s_nop 0
	global_load_lds_dwordx4 v[138:139], off
	v_lshl_add_u64 v[138:139], s[36:37], 0, v[128:129]
	s_add_i32 m0, s4, 0x2000
	s_nop 0
	global_load_lds_dwordx4 v[138:139], off
	v_lshl_add_u64 v[138:139], v[240:241], 0, s[62:63]
	s_mov_b32 m0, s28
	s_nop 0
	global_load_lds_dwordx4 v[138:139], off
	v_lshl_add_u64 v[138:139], v[242:243], 0, s[62:63]
	s_mov_b32 m0, s29
	s_nop 0
	global_load_lds_dwordx4 v[138:139], off
	s_waitcnt vmcnt(8)
	s_waitcnt lgkmcnt(0)
	s_barrier
	v_mfma_f32_16x16x32_f16 v[60:63], v[144:147], v[188:191], v[60:63]
	v_mfma_f32_16x16x32_f16 v[48:51], v[152:155], v[188:191], v[48:51]
	v_mfma_f32_16x16x32_f16 v[44:47], v[144:147], v[214:217], v[44:47]
	v_mfma_f32_16x16x32_f16 v[32:35], v[152:155], v[214:217], v[32:35]
	v_mfma_f32_16x16x32_f16 v[28:31], v[144:147], v[222:225], v[28:31]
	v_mfma_f32_16x16x32_f16 v[16:19], v[152:155], v[222:225], v[16:19]
	v_mfma_f32_16x16x32_f16 v[12:15], v[144:147], v[230:233], v[12:15]
	v_mfma_f32_16x16x32_f16 v[0:3], v[152:155], v[230:233], v[0:3]
	v_mfma_f32_16x16x32_f16 v[60:63], v[148:151], v[192:195], v[60:63]
	v_mfma_f32_16x16x32_f16 v[48:51], v[156:159], v[192:195], v[48:51]
	v_mfma_f32_16x16x32_f16 v[44:47], v[148:151], v[218:221], v[44:47]
	v_mfma_f32_16x16x32_f16 v[32:35], v[156:159], v[218:221], v[32:35]
	v_mfma_f32_16x16x32_f16 v[28:31], v[148:151], v[226:229], v[28:31]
	v_mfma_f32_16x16x32_f16 v[16:19], v[156:159], v[226:229], v[16:19]
	v_mfma_f32_16x16x32_f16 v[12:15], v[148:151], v[234:237], v[12:15]
	v_mfma_f32_16x16x32_f16 v[0:3], v[156:159], v[234:237], v[0:3]
	v_mfma_f32_16x16x32_f16 v[56:59], v[172:175], v[188:191], v[56:59]
	v_mfma_f32_16x16x32_f16 v[52:55], v[180:183], v[188:191], v[52:55]
	v_mfma_f32_16x16x32_f16 v[40:43], v[172:175], v[214:217], v[40:43]
	v_mfma_f32_16x16x32_f16 v[36:39], v[180:183], v[214:217], v[36:39]
	v_mfma_f32_16x16x32_f16 v[24:27], v[172:175], v[222:225], v[24:27]
	v_mfma_f32_16x16x32_f16 v[20:23], v[180:183], v[222:225], v[20:23]
	v_mfma_f32_16x16x32_f16 v[8:11], v[172:175], v[230:233], v[8:11]
	v_mfma_f32_16x16x32_f16 v[4:7], v[180:183], v[230:233], v[4:7]
	v_mfma_f32_16x16x32_f16 v[56:59], v[176:179], v[192:195], v[56:59]
	v_mfma_f32_16x16x32_f16 v[52:55], v[184:187], v[192:195], v[52:55]
	v_mfma_f32_16x16x32_f16 v[40:43], v[176:179], v[218:221], v[40:43]
	v_mfma_f32_16x16x32_f16 v[36:39], v[184:187], v[218:221], v[36:39]
	v_mfma_f32_16x16x32_f16 v[24:27], v[176:179], v[226:229], v[24:27]
	v_mfma_f32_16x16x32_f16 v[20:23], v[184:187], v[226:229], v[20:23]
	v_mfma_f32_16x16x32_f16 v[8:11], v[176:179], v[234:237], v[8:11]
	v_mfma_f32_16x16x32_f16 v[4:7], v[184:187], v[234:237], v[4:7]
	s_barrier
	s_add_i32 s71, s71, 2
	s_add_u32 s50, s50, 0x100
	s_addc_u32 s51, s51, 0
	s_add_u32 s69, s69, 0x100
	s_addc_u32 s70, s70, 0
	s_cmp_gt_u32 s71, 13
	s_cbranch_scc0 .LBB0_396
	s_and_b64 vcc, exec, s[40:41]
	s_cbranch_vccz .LBB0_399
	s_barrier

; #define PG8_STAGE(bufoff, gbase, voff) do { _Pragma("unroll") for (int _i = 0; _i < 2; ++_i) \
;         __builtin_amdgcn_global_load_lds((const unsigned*)((const char*)(gbase) + (voff)[_i]), (LAS unsigned*)(lds + (bufoff) + ldsw + _i * 8192), 16, 0, 0); } while (0)
; #define PG8_LDA(dst, b, h) do { _Pragma("unroll") for (int m = 0; m < 4; ++m) _Pragma("unroll") for (int k = 0; k < 2; ++k) dst[m][k] = *(const LAS bf16x8*)(lds + PG8_SA(b, h) + aoff + m * 2048 + k * 1024); } while (0)
; #define PG8_LDB(dst, b, h) do { _Pragma("unroll") for (int n = 0; n < 2; ++n) _Pragma("unroll") for (int k = 0; k < 2; ++k) dst[n][k] = *(const LAS bf16x8*)(lds + PG8_SB(b, h) + boff + n * 2048 + k * 1024); } while (0)
; #define PG8_WAIT_V(n) asm volatile("s_waitcnt vmcnt(" #n ")" ::: "memory")
; #define PG8_WAIT_L(n) asm volatile("s_waitcnt lgkmcnt(" #n ")" ::: "memory")
; #define PG8_BAR __builtin_amdgcn_s_barrier()
; #define PG8_SCHED __builtin_amdgcn_sched_barrier(0)
; template <class Epi>
; __device__ __forceinline__ void gemm_phase(LAS unsigned char* lds, const Gemm g, const Order& S, const Epi& E) {
;     ...
;             const bool last = (t == nt - 2);
;             const char* a1 = cA + (size_t)(t + 1) * kstep;
;             const char* a2 = last ? nA : cA + (size_t)(t + 2) * kstep; const char* b2 = last ? nB : cB + (size_t)(t + 2) * kstep;
;             const char* a3 = a2 + kstep; const char* b3 = b2 + kstep;
;             PG8_LDB(B0, 0, 0); PG8_LDB(B1, 0, 1); PG8_SCHED; PG8_LDA(At, 0, 0); PG8_STAGE(PG8_SA(1, 1), a1 + hstepA, voffA);
;             PG8_WAIT_V(8); PG8_WAIT_L(0); PG8_BAR; PG8_MMA(0, 0, At, B0); PG8_MMA(0, 1, At, B1); PG8_BAR; PG8_SCHED;
;             PG8_LDA(At, 0, 1); PG8_STAGE(PG8_SB(0, 0), b2, voffB); PG8_STAGE(PG8_SB(0, 1), b2 + hstepB, voffB); PG8_STAGE(PG8_SA(0, 0), a2, voffA);
;             PG8_WAIT_V(8); PG8_WAIT_L(0); PG8_BAR; PG8_MMA(1, 0, At, B0); PG8_MMA(1, 1, At, B1); PG8_BAR; PG8_SCHED;
.LBB0_413:
	s_add_u32 s4, s48, 0xfffc0080
	s_addc_u32 s5, s49, -1
	s_add_i32 s36, 0, 0x10000
	s_cmp_eq_u32 s66, 12
	s_cselect_b32 s65, s30, s5
	s_cselect_b32 s64, s31, s4
	v_add_u32_e32 v138, s36, v141
	s_cselect_b32 s51, s34, s43
	s_cselect_b32 s50, s35, s41
	s_add_i32 s4, 0, 0x14000
	ds_read_b128 v[144:147], v138
	ds_read_b128 v[148:151], v138 offset:1024
	ds_read_b128 v[152:155], v138 offset:2048
	ds_read_b128 v[156:159], v138 offset:3072
	v_add_u32_e32 v138, s4, v141
	ds_read_b128 v[172:175], v138
	ds_read_b128 v[176:179], v138 offset:1024
	ds_read_b128 v[180:183], v138 offset:2048
	ds_read_b128 v[184:187], v138 offset:3072
	v_lshl_add_u64 v[138:139], s[48:49], 0, v[134:135]
	s_add_i32 m0, s21, 0xc000
	ds_read_b128 v[188:191], v143
	ds_read_b128 v[192:195], v143 offset:1024
	ds_read_b128 v[214:217], v143 offset:2048
	ds_read_b128 v[218:221], v143 offset:3072
	ds_read_b128 v[222:225], v143 offset:4096
	ds_read_b128 v[226:229], v143 offset:5120
	ds_read_b128 v[230:233], v143 offset:6144
	ds_read_b128 v[234:237], v143 offset:7168
	global_load_lds_dwordx4 v[138:139], off
	v_lshl_add_u64 v[138:139], s[48:49], 0, v[136:137]
	s_add_i32 m0, s21, 0xe000
	s_nop 0
	global_load_lds_dwordx4 v[138:139], off
	s_waitcnt vmcnt(8)
	s_waitcnt lgkmcnt(0)
	s_barrier
	v_mfma_f32_16x16x32_bf16 v[124:127], v[144:147], v[188:191], v[124:127]
	v_mfma_f32_16x16x32_bf16 v[120:123], v[152:155], v[188:191], v[120:123]
	v_mfma_f32_16x16x32_bf16 v[116:119], v[144:147], v[214:217], v[116:119]
	v_mfma_f32_16x16x32_bf16 v[108:111], v[152:155], v[214:217], v[108:111]
	v_mfma_f32_16x16x32_bf16 v[100:103], v[144:147], v[222:225], v[100:103]
	v_mfma_f32_16x16x32_bf16 v[92:95], v[152:155], v[222:225], v[92:95]
	v_mfma_f32_16x16x32_bf16 v[84:87], v[144:147], v[230:233], v[84:87]
	v_mfma_f32_16x16x32_bf16 v[76:79], v[152:155], v[230:233], v[76:79]
	v_mfma_f32_16x16x32_bf16 v[124:127], v[148:151], v[192:195], v[124:127]
	v_mfma_f32_16x16x32_bf16 v[120:123], v[156:159], v[192:195], v[120:123]
	v_mfma_f32_16x16x32_bf16 v[116:119], v[148:151], v[218:221], v[116:119]
	v_mfma_f32_16x16x32_bf16 v[108:111], v[156:159], v[218:221], v[108:111]
	v_mfma_f32_16x16x32_bf16 v[100:103], v[148:151], v[226:229], v[100:103]
	v_mfma_f32_16x16x32_bf16 v[92:95], v[156:159], v[226:229], v[92:95]
	v_mfma_f32_16x16x32_bf16 v[84:87], v[148:151], v[234:237], v[84:87]
	v_mfma_f32_16x16x32_bf16 v[76:79], v[156:159], v[234:237], v[76:79]
	v_mfma_f32_16x16x32_bf16 v[112:115], v[172:175], v[188:191], v[112:115]
	v_mfma_f32_16x16x32_bf16 v[104:107], v[180:183], v[188:191], v[104:107]
	v_mfma_f32_16x16x32_bf16 v[96:99], v[172:175], v[214:217], v[96:99]
	v_mfma_f32_16x16x32_bf16 v[88:91], v[180:183], v[214:217], v[88:91]
	v_mfma_f32_16x16x32_bf16 v[80:83], v[172:175], v[222:225], v[80:83]
	v_mfma_f32_16x16x32_bf16 v[72:75], v[180:183], v[222:225], v[72:75]
	v_mfma_f32_16x16x32_bf16 v[68:71], v[172:175], v[230:233], v[68:71]
	v_mfma_f32_16x16x32_bf16 v[64:67], v[180:183], v[230:233], v[64:67]
	v_mfma_f32_16x16x32_bf16 v[112:115], v[176:179], v[192:195], v[112:115]
	v_mfma_f32_16x16x32_bf16 v[104:107], v[184:187], v[192:195], v[104:107]
	v_mfma_f32_16x16x32_bf16 v[96:99], v[176:179], v[218:221], v[96:99]
	v_mfma_f32_16x16x32_bf16 v[88:91], v[184:187], v[218:221], v[88:91]
	v_mfma_f32_16x16x32_bf16 v[80:83], v[176:179], v[226:229], v[80:83]
	v_mfma_f32_16x16x32_bf16 v[72:75], v[184:187], v[226:229], v[72:75]
	v_mfma_f32_16x16x32_bf16 v[68:71], v[176:179], v[234:237], v[68:71]
	v_mfma_f32_16x16x32_bf16 v[64:67], v[184:187], v[234:237], v[64:67]
	s_barrier
	s_add_i32 s5, s36, s1
	v_lshl_add_u64 v[138:139], s[50:51], 0, v[160:161]
	s_mov_b32 m0, s5
	ds_read_b128 v[188:191], v143 offset:16384
	ds_read_b128 v[192:195], v143 offset:17408
	ds_read_b128 v[214:217], v143 offset:18432
	ds_read_b128 v[218:221], v143 offset:19456
	ds_read_b128 v[222:225], v143 offset:20480
	ds_read_b128 v[226:229], v143 offset:21504
	ds_read_b128 v[230:233], v143 offset:22528
	ds_read_b128 v[234:237], v143 offset:23552
	global_load_lds_dwordx4 v[138:139], off
	s_add_i32 m0, s5, 0x2000
	s_add_u32 s36, s50, 0x40000
	v_lshl_add_u64 v[238:239], s[50:51], 0, v[128:129]
	s_addc_u32 s37, s51, 0
	s_add_i32 s4, s4, s1
	global_load_lds_dwordx4 v[238:239], off
	v_lshl_add_u64 v[240:241], s[36:37], 0, v[160:161]
	s_mov_b32 m0, s4
	v_lshl_add_u64 v[242:243], s[64:65], 0, v[130:131]
	global_load_lds_dwordx4 v[240:241], off
	v_lshl_add_u64 v[240:241], s[36:37], 0, v[128:129]
	s_add_i32 m0, s4, 0x2000
	s_nop 0
	global_load_lds_dwordx4 v[240:241], off
	v_lshl_add_u64 v[240:241], s[64:65], 0, v[132:133]
	s_mov_b32 m0, s21
	s_nop 0
	global_load_lds_dwordx4 v[240:241], off
	s_mov_b32 m0, s22
	s_nop 0
	global_load_lds_dwordx4 v[242:243], off
	s_waitcnt vmcnt(8)
	s_waitcnt lgkmcnt(0)
	s_barrier
; #define PG8_STAGE(bufoff, gbase, voff) do { _Pragma("unroll") for (int _i = 0; _i < 2; ++_i) \
;         __builtin_amdgcn_global_load_lds((const unsigned*)((const char*)(gbase) + (voff)[_i]), (LAS unsigned*)(lds + (bufoff) + ldsw + _i * 8192), 16, 0, 0); } while (0)
; #define PG8_LDA(dst, b, h) do { _Pragma("unroll") for (int m = 0; m < 4; ++m) _Pragma("unroll") for (int k = 0; k < 2; ++k) dst[m][k] = *(const LAS bf16x8*)(lds + PG8_SA(b, h) + aoff + m * 2048 + k * 1024); } while (0)
; #define PG8_LDB(dst, b, h) do { _Pragma("unroll") for (int n = 0; n < 2; ++n) _Pragma("unroll") for (int k = 0; k < 2; ++k) dst[n][k] = *(const LAS bf16x8*)(lds + PG8_SB(b, h) + boff + n * 2048 + k * 1024); } while (0)
; #define PG8_WAIT_V(n) asm volatile("s_waitcnt vmcnt(" #n ")" ::: "memory")
; #define PG8_WAIT_L(n) asm volatile("s_waitcnt lgkmcnt(" #n ")" ::: "memory")
; #define PG8_BAR __builtin_amdgcn_s_barrier()
; #define PG8_SCHED __builtin_amdgcn_sched_barrier(0)
; template <class Epi>
; __device__ __forceinline__ void gemm_phase(LAS unsigned char* lds, const Gemm g, const Order& S, const Epi& E) {
;     ...
;             PG8_WAIT_V(8); PG8_WAIT_L(0); PG8_BAR; PG8_MMA(1, 0, At, B0); PG8_MMA(1, 1, At, B1); PG8_BAR; PG8_SCHED;
;             PG8_LDB(B0, 1, 0); PG8_LDB(B1, 1, 1); PG8_SCHED; PG8_LDA(At, 1, 0); PG8_STAGE(PG8_SA(0, 1), a2 + hstepA, voffA);
;             PG8_WAIT_V(8); PG8_WAIT_L(0); PG8_BAR; PG8_MMA(0, 0, At, B0); PG8_MMA(0, 1, At, B1); PG8_BAR; PG8_SCHED;
	v_mfma_f32_16x16x32_bf16 v[60:63], v[144:147], v[188:191], v[60:63]
	v_mfma_f32_16x16x32_bf16 v[56:59], v[152:155], v[188:191], v[56:59]
	v_mfma_f32_16x16x32_bf16 v[52:55], v[144:147], v[214:217], v[52:55]
	v_mfma_f32_16x16x32_bf16 v[44:47], v[152:155], v[214:217], v[44:47]
	v_mfma_f32_16x16x32_bf16 v[36:39], v[144:147], v[222:225], v[36:39]
	v_mfma_f32_16x16x32_bf16 v[28:31], v[152:155], v[222:225], v[28:31]
	v_mfma_f32_16x16x32_bf16 v[20:23], v[144:147], v[230:233], v[20:23]
	v_mfma_f32_16x16x32_bf16 v[12:15], v[152:155], v[230:233], v[12:15]
	v_mfma_f32_16x16x32_bf16 v[60:63], v[148:151], v[192:195], v[60:63]
	v_mfma_f32_16x16x32_bf16 v[56:59], v[156:159], v[192:195], v[56:59]
	v_mfma_f32_16x16x32_bf16 v[52:55], v[148:151], v[218:221], v[52:55]
	v_mfma_f32_16x16x32_bf16 v[44:47], v[156:159], v[218:221], v[44:47]
	v_mfma_f32_16x16x32_bf16 v[36:39], v[148:151], v[226:229], v[36:39]
	v_mfma_f32_16x16x32_bf16 v[28:31], v[156:159], v[226:229], v[28:31]
	v_mfma_f32_16x16x32_bf16 v[20:23], v[148:151], v[234:237], v[20:23]
	v_mfma_f32_16x16x32_bf16 v[12:15], v[156:159], v[234:237], v[12:15]
	v_mfma_f32_16x16x32_bf16 v[48:51], v[172:175], v[188:191], v[48:51]
	v_mfma_f32_16x16x32_bf16 v[40:43], v[180:183], v[188:191], v[40:43]
	v_mfma_f32_16x16x32_bf16 v[32:35], v[172:175], v[214:217], v[32:35]
	v_mfma_f32_16x16x32_bf16 v[24:27], v[180:183], v[214:217], v[24:27]
	v_mfma_f32_16x16x32_bf16 v[16:19], v[172:175], v[222:225], v[16:19]
	v_mfma_f32_16x16x32_bf16 v[8:11], v[180:183], v[222:225], v[8:11]
	v_mfma_f32_16x16x32_bf16 v[4:7], v[172:175], v[230:233], v[4:7]
	v_mfma_f32_16x16x32_bf16 v[0:3], v[180:183], v[230:233], v[0:3]
	v_mfma_f32_16x16x32_bf16 v[48:51], v[176:179], v[192:195], v[48:51]
	v_mfma_f32_16x16x32_bf16 v[40:43], v[184:187], v[192:195], v[40:43]
	v_mfma_f32_16x16x32_bf16 v[32:35], v[176:179], v[218:221], v[32:35]
	v_mfma_f32_16x16x32_bf16 v[24:27], v[184:187], v[218:221], v[24:27]
	v_mfma_f32_16x16x32_bf16 v[16:19], v[176:179], v[226:229], v[16:19]
	v_mfma_f32_16x16x32_bf16 v[8:11], v[184:187], v[226:229], v[8:11]
	v_mfma_f32_16x16x32_bf16 v[4:7], v[176:179], v[234:237], v[4:7]
	v_mfma_f32_16x16x32_bf16 v[0:3], v[184:187], v[234:237], v[0:3]
	s_barrier
	s_add_i32 s4, 0, 0x18000
	s_add_i32 s5, 0, 0x1c000
	v_add_u32_e32 v156, s4, v141
	v_add_u32_e32 v171, s5, v141
	ds_read_b128 v[144:147], v156
	ds_read_b128 v[148:151], v156 offset:1024
	ds_read_b128 v[152:155], v156 offset:2048
	ds_read_b128 v[156:159], v156 offset:3072
	ds_read_b128 v[172:175], v171
	ds_read_b128 v[176:179], v171 offset:1024
	ds_read_b128 v[180:183], v171 offset:2048
	ds_read_b128 v[184:187], v171 offset:3072
	s_add_u32 s36, s64, 0x40000
	s_addc_u32 s37, s65, 0
	s_mov_b32 m0, s23
	v_lshl_add_u64 v[244:245], s[36:37], 0, v[132:133]
	ds_read_b128 v[188:191], v143 offset:32768
	ds_read_b128 v[192:195], v143 offset:33792
	ds_read_b128 v[214:217], v143 offset:34816
	ds_read_b128 v[218:221], v143 offset:35840
	ds_read_b128 v[222:225], v143 offset:36864
	ds_read_b128 v[226:229], v143 offset:37888
	ds_read_b128 v[230:233], v143 offset:38912
	ds_read_b128 v[234:237], v143 offset:39936
	global_load_lds_dwordx4 v[244:245], off
	v_lshl_add_u64 v[244:245], s[36:37], 0, v[130:131]
	s_mov_b32 m0, s24
	s_nop 0
	global_load_lds_dwordx4 v[244:245], off
	s_waitcnt vmcnt(8)
	s_waitcnt lgkmcnt(0)
	s_barrier
	v_mfma_f32_16x16x32_bf16 v[124:127], v[144:147], v[188:191], v[124:127]
	v_mfma_f32_16x16x32_bf16 v[120:123], v[152:155], v[188:191], v[120:123]
	v_mfma_f32_16x16x32_bf16 v[116:119], v[144:147], v[214:217], v[116:119]
	v_mfma_f32_16x16x32_bf16 v[108:111], v[152:155], v[214:217], v[108:111]
	v_mfma_f32_16x16x32_bf16 v[100:103], v[144:147], v[222:225], v[100:103]
	v_mfma_f32_16x16x32_bf16 v[92:95], v[152:155], v[222:225], v[92:95]
	v_mfma_f32_16x16x32_bf16 v[84:87], v[144:147], v[230:233], v[84:87]
	v_mfma_f32_16x16x32_bf16 v[76:79], v[152:155], v[230:233], v[76:79]
	v_mfma_f32_16x16x32_bf16 v[124:127], v[148:151], v[192:195], v[124:127]
	v_mfma_f32_16x16x32_bf16 v[120:123], v[156:159], v[192:195], v[120:123]
	v_mfma_f32_16x16x32_bf16 v[116:119], v[148:151], v[218:221], v[116:119]
	v_mfma_f32_16x16x32_bf16 v[108:111], v[156:159], v[218:221], v[108:111]
	v_mfma_f32_16x16x32_bf16 v[100:103], v[148:151], v[226:229], v[100:103]
	v_mfma_f32_16x16x32_bf16 v[92:95], v[156:159], v[226:229], v[92:95]
	v_mfma_f32_16x16x32_bf16 v[84:87], v[148:151], v[234:237], v[84:87]
	v_mfma_f32_16x16x32_bf16 v[76:79], v[156:159], v[234:237], v[76:79]
	v_mfma_f32_16x16x32_bf16 v[112:115], v[172:175], v[188:191], v[112:115]
	v_mfma_f32_16x16x32_bf16 v[104:107], v[180:183], v[188:191], v[104:107]
	v_mfma_f32_16x16x32_bf16 v[96:99], v[172:175], v[214:217], v[96:99]
	v_mfma_f32_16x16x32_bf16 v[88:91], v[180:183], v[214:217], v[88:91]
	v_mfma_f32_16x16x32_bf16 v[80:83], v[172:175], v[222:225], v[80:83]
	v_mfma_f32_16x16x32_bf16 v[72:75], v[180:183], v[222:225], v[72:75]
	v_mfma_f32_16x16x32_bf16 v[68:71], v[172:175], v[230:233], v[68:71]
	v_mfma_f32_16x16x32_bf16 v[64:67], v[180:183], v[230:233], v[64:67]
	v_mfma_f32_16x16x32_bf16 v[112:115], v[176:179], v[192:195], v[112:115]
	v_mfma_f32_16x16x32_bf16 v[104:107], v[184:187], v[192:195], v[104:107]
	v_mfma_f32_16x16x32_bf16 v[96:99], v[176:179], v[218:221], v[96:99]
	v_mfma_f32_16x16x32_bf16 v[88:91], v[184:187], v[218:221], v[88:91]
	v_mfma_f32_16x16x32_bf16 v[80:83], v[176:179], v[226:229], v[80:83]
	v_mfma_f32_16x16x32_bf16 v[72:75], v[184:187], v[226:229], v[72:75]
	v_mfma_f32_16x16x32_bf16 v[68:71], v[176:179], v[234:237], v[68:71]
	v_mfma_f32_16x16x32_bf16 v[64:67], v[184:187], v[234:237], v[64:67]
	s_barrier
; #define PG8_STAGE(bufoff, gbase, voff) do { _Pragma("unroll") for (int _i = 0; _i < 2; ++_i) \
;         __builtin_amdgcn_global_load_lds((const unsigned*)((const char*)(gbase) + (voff)[_i]), (LAS unsigned*)(lds + (bufoff) + ldsw + _i * 8192), 16, 0, 0); } while (0)
; #define PG8_LDA(dst, b, h) do { _Pragma("unroll") for (int m = 0; m < 4; ++m) _Pragma("unroll") for (int k = 0; k < 2; ++k) dst[m][k] = *(const LAS bf16x8*)(lds + PG8_SA(b, h) + aoff + m * 2048 + k * 1024); } while (0)
; #define PG8_WAIT_V(n) asm volatile("s_waitcnt vmcnt(" #n ")" ::: "memory")
; #define PG8_WAIT_L(n) asm volatile("s_waitcnt lgkmcnt(" #n ")" ::: "memory")
; #define PG8_BAR __builtin_amdgcn_s_barrier()
; #define PG8_SCHED __builtin_amdgcn_sched_barrier(0)
; template <class Epi>
; __device__ __forceinline__ void gemm_phase(LAS unsigned char* lds, const Gemm g, const Order& S, const Epi& E) {
;     ...
;             PG8_LDA(At, 1, 1); PG8_STAGE(PG8_SB(1, 0), b3, voffB); PG8_STAGE(PG8_SB(1, 1), b3 + hstepB, voffB); PG8_STAGE(PG8_SA(1, 0), a3, voffA);
;             PG8_WAIT_V(8); PG8_WAIT_L(0); PG8_BAR; PG8_MMA(1, 0, At, B0); PG8_MMA(1, 1, At, B1); PG8_BAR; PG8_SCHED;
;         }
;         if constexpr (ALIGN_EPI) { if (wr == 0) PG8_BAR; }
;         if constexpr (!Epi::AFTER_DRAIN) E(acc, cur, wr, wc, fr, fq);
;         if (!has_next) break;
	s_add_i32 s4, s4, s1
	v_lshl_add_u64 v[138:139], v[138:139], 0, s[62:63]
	s_mov_b32 m0, s4
	ds_read_b128 v[188:191], v143 offset:49152
	ds_read_b128 v[192:195], v143 offset:50176
	ds_read_b128 v[214:217], v143 offset:51200
	ds_read_b128 v[218:221], v143 offset:52224
	ds_read_b128 v[222:225], v143 offset:53248
	ds_read_b128 v[226:229], v143 offset:54272
	ds_read_b128 v[230:233], v143 offset:55296
	ds_read_b128 v[234:237], v143 offset:56320
	global_load_lds_dwordx4 v[138:139], off
	s_add_i32 m0, s4, 0x2000
	s_add_u32 s36, s50, 0x40080
	v_lshl_add_u64 v[138:139], v[238:239], 0, s[62:63]
	s_addc_u32 s37, s51, 0
	s_add_i32 s4, s5, s1
	global_load_lds_dwordx4 v[138:139], off
	v_lshl_add_u64 v[138:139], s[36:37], 0, v[160:161]
	s_mov_b32 m0, s4
	s_nop 0
	global_load_lds_dwordx4 v[138:139], off
	v_lshl_add_u64 v[138:139], s[36:37], 0, v[128:129]
	s_add_i32 m0, s4, 0x2000
	s_nop 0
	global_load_lds_dwordx4 v[138:139], off
	v_lshl_add_u64 v[138:139], v[240:241], 0, s[62:63]
	s_mov_b32 m0, s25
	s_nop 0
	global_load_lds_dwordx4 v[138:139], off
	v_lshl_add_u64 v[138:139], v[242:243], 0, s[62:63]
	s_mov_b32 m0, s26
	s_nop 0
	global_load_lds_dwordx4 v[138:139], off
	s_waitcnt vmcnt(8)
	s_waitcnt lgkmcnt(0)
	s_barrier
	v_mfma_f32_16x16x32_bf16 v[60:63], v[144:147], v[188:191], v[60:63]
	v_mfma_f32_16x16x32_bf16 v[56:59], v[152:155], v[188:191], v[56:59]
	v_mfma_f32_16x16x32_bf16 v[52:55], v[144:147], v[214:217], v[52:55]
	v_mfma_f32_16x16x32_bf16 v[44:47], v[152:155], v[214:217], v[44:47]
	v_mfma_f32_16x16x32_bf16 v[36:39], v[144:147], v[222:225], v[36:39]
	v_mfma_f32_16x16x32_bf16 v[28:31], v[152:155], v[222:225], v[28:31]
	v_mfma_f32_16x16x32_bf16 v[20:23], v[144:147], v[230:233], v[20:23]
	v_mfma_f32_16x16x32_bf16 v[12:15], v[152:155], v[230:233], v[12:15]
	v_mfma_f32_16x16x32_bf16 v[60:63], v[148:151], v[192:195], v[60:63]
	v_mfma_f32_16x16x32_bf16 v[56:59], v[156:159], v[192:195], v[56:59]
	v_mfma_f32_16x16x32_bf16 v[52:55], v[148:151], v[218:221], v[52:55]
	v_mfma_f32_16x16x32_bf16 v[44:47], v[156:159], v[218:221], v[44:47]
	v_mfma_f32_16x16x32_bf16 v[36:39], v[148:151], v[226:229], v[36:39]
	v_mfma_f32_16x16x32_bf16 v[28:31], v[156:159], v[226:229], v[28:31]
	v_mfma_f32_16x16x32_bf16 v[20:23], v[148:151], v[234:237], v[20:23]
	v_mfma_f32_16x16x32_bf16 v[12:15], v[156:159], v[234:237], v[12:15]
	v_mfma_f32_16x16x32_bf16 v[48:51], v[172:175], v[188:191], v[48:51]
	v_mfma_f32_16x16x32_bf16 v[40:43], v[180:183], v[188:191], v[40:43]
	v_mfma_f32_16x16x32_bf16 v[32:35], v[172:175], v[214:217], v[32:35]
	v_mfma_f32_16x16x32_bf16 v[24:27], v[180:183], v[214:217], v[24:27]
	v_mfma_f32_16x16x32_bf16 v[16:19], v[172:175], v[222:225], v[16:19]
	v_mfma_f32_16x16x32_bf16 v[8:11], v[180:183], v[222:225], v[8:11]
	v_mfma_f32_16x16x32_bf16 v[4:7], v[172:175], v[230:233], v[4:7]
	v_mfma_f32_16x16x32_bf16 v[0:3], v[180:183], v[230:233], v[0:3]
	v_mfma_f32_16x16x32_bf16 v[48:51], v[176:179], v[192:195], v[48:51]
	v_mfma_f32_16x16x32_bf16 v[40:43], v[184:187], v[192:195], v[40:43]
	v_mfma_f32_16x16x32_bf16 v[32:35], v[176:179], v[218:221], v[32:35]
	v_mfma_f32_16x16x32_bf16 v[24:27], v[184:187], v[218:221], v[24:27]
	v_mfma_f32_16x16x32_bf16 v[16:19], v[176:179], v[226:229], v[16:19]
	v_mfma_f32_16x16x32_bf16 v[8:11], v[184:187], v[226:229], v[8:11]
	v_mfma_f32_16x16x32_bf16 v[4:7], v[176:179], v[234:237], v[4:7]
	v_mfma_f32_16x16x32_bf16 v[0:3], v[184:187], v[234:237], v[0:3]
	s_barrier
	s_add_i32 s66, s66, 2
	s_add_u32 s48, s48, 0x100
	s_addc_u32 s49, s49, 0
	s_add_u32 s41, s41, 0x100
	s_addc_u32 s43, s43, 0
	s_cmp_gt_u32 s66, 13
	s_cbranch_scc0 .LBB0_413
	s_and_b64 vcc, exec, s[12:13]
	s_cbranch_vccz .LBB0_416
	s_barrier

; __device__ __forceinline__ void xcd_barrier(const XcdBarrier& b) {
;     asm volatile("s_waitcnt vmcnt(0)" ::: "memory");
;     __syncthreads();
;     if (threadIdx.x == 0) {
;         unsigned* bar = b.bar;
;         __builtin_amdgcn_s_waitcnt(0);
;         unsigned nloc = b.st[0], nx = b.st[1];
;         if (nloc == 0u) { xcd_barrier_complete(bar, b.x, nloc, nx); b.st[0] = nloc; b.st[1] = nx; }
.LBB0_471:
	s_setprio 0
	s_waitcnt vmcnt(0)
	s_waitcnt vmcnt(0)
	s_barrier
	s_mov_b64 s[0:1], exec
	v_readlane_b32 s4, v253, 2
	v_readlane_b32 s5, v253, 3
	s_and_b64 s[4:5], s[0:1], s[4:5]
	s_mov_b64 exec, s[4:5]
	s_cbranch_execz .LBB0_17
	v_readlane_b32 s4, v254, 52
	s_waitcnt vmcnt(0) expcnt(0) lgkmcnt(0)
	s_nop 0
	v_mov_b32_e32 v0, s4
	ds_read_b32 v2, v0
	v_readlane_b32 s4, v254, 53
	s_waitcnt lgkmcnt(0)
	v_cmp_ne_u32_e32 vcc, 0, v2
	v_mov_b32_e32 v0, s4
	ds_read_b32 v0, v0
	s_cbranch_vccnz .LBB0_487
	s_mov_b32 s21, 1
	s_branch .LBB0_475
